# plus: retention in-projection GEMM epilogue (EpiRetIn) hand-written: column class and row kind decided once per unit instead of per fragment
# speedup vs baseline: 1.0218x; 1.0159x over previous
.LBB0_474:
	ds_read_b128 v[144:147], v167
	ds_read_b128 v[148:151], v167 offset:1024
	ds_read_b128 v[152:155], v167 offset:2048
	ds_read_b128 v[156:159], v167 offset:3072
	s_add_u32 s24, s22, 0xfffc0080
	s_addc_u32 s25, s23, -1
	s_cmp_eq_u32 s51, 12
	s_cselect_b32 s27, s7, s25
	s_cselect_b32 s26, s17, s24
	s_cselect_b32 s25, s9, s50
	s_cselect_b32 s24, s28, s29
	v_lshl_add_u64 v[160:161], s[22:23], 0, v[136:137]
	s_add_i32 m0, s1, 0xc000
	ds_read_b128 v[172:175], v168
	ds_read_b128 v[176:179], v168 offset:1024
	ds_read_b128 v[180:183], v168 offset:2048
	ds_read_b128 v[184:187], v168 offset:3072
	ds_read_b128 v[188:191], v168 offset:4096
	ds_read_b128 v[192:195], v168 offset:5120
	ds_read_b128 v[196:199], v168 offset:6144
	ds_read_b128 v[200:203], v168 offset:7168
	global_load_lds_dwordx4 v[160:161], off
	v_lshl_add_u64 v[160:161], s[22:23], 0, v[138:139]
	s_add_i32 m0, s1, 0xe000
	s_nop 0
	global_load_lds_dwordx4 v[160:161], off
	s_waitcnt lgkmcnt(8)
	s_barrier
	s_waitcnt lgkmcnt(0)
	s_setprio 1
	s_waitcnt lgkmcnt(0)
	v_mfma_f32_16x16x32_bf16 v[126:129], v[144:147], v[172:175], v[126:129]
	v_mfma_f32_16x16x32_bf16 v[122:125], v[152:155], v[172:175], v[122:125]
	v_mfma_f32_16x16x32_bf16 v[110:113], v[144:147], v[180:183], v[110:113]
	v_mfma_f32_16x16x32_bf16 v[106:109], v[152:155], v[180:183], v[106:109]
	v_mfma_f32_16x16x32_bf16 v[94:97], v[144:147], v[188:191], v[94:97]
	v_mfma_f32_16x16x32_bf16 v[90:93], v[152:155], v[188:191], v[90:93]
	v_mfma_f32_16x16x32_bf16 v[78:81], v[144:147], v[196:199], v[78:81]
	v_mfma_f32_16x16x32_bf16 v[74:77], v[152:155], v[196:199], v[74:77]
	v_mfma_f32_16x16x32_bf16 v[126:129], v[148:151], v[176:179], v[126:129]
	v_mfma_f32_16x16x32_bf16 v[122:125], v[156:159], v[176:179], v[122:125]
	v_mfma_f32_16x16x32_bf16 v[110:113], v[148:151], v[184:187], v[110:113]
	v_mfma_f32_16x16x32_bf16 v[106:109], v[156:159], v[184:187], v[106:109]
	v_mfma_f32_16x16x32_bf16 v[94:97], v[148:151], v[192:195], v[94:97]
	v_mfma_f32_16x16x32_bf16 v[90:93], v[156:159], v[192:195], v[90:93]
	v_mfma_f32_16x16x32_bf16 v[78:81], v[148:151], v[200:203], v[78:81]
	v_mfma_f32_16x16x32_bf16 v[74:77], v[156:159], v[200:203], v[74:77]
	s_setprio 0
	s_barrier
	s_add_i32 s52, s45, s34
	v_lshl_add_u64 v[160:161], s[24:25], 0, v[130:131]
	s_mov_b32 m0, s52
	ds_read_b128 v[204:207], v169
	ds_read_b128 v[208:211], v169 offset:1024
	ds_read_b128 v[212:215], v169 offset:2048
	ds_read_b128 v[216:219], v169 offset:3072
	global_load_lds_dwordx4 v[160:161], off
	v_lshl_add_u64 v[220:221], s[24:25], 0, v[132:133]
	s_add_i32 m0, s52, 0x2000
	s_nop 0
	global_load_lds_dwordx4 v[220:221], off
	s_barrier
	s_waitcnt lgkmcnt(0)
	s_setprio 1
	s_waitcnt lgkmcnt(0)
	v_mfma_f32_16x16x32_bf16 v[118:121], v[204:207], v[172:175], v[118:121]
	v_mfma_f32_16x16x32_bf16 v[114:117], v[212:215], v[172:175], v[114:117]
	v_mfma_f32_16x16x32_bf16 v[102:105], v[204:207], v[180:183], v[102:105]
	v_mfma_f32_16x16x32_bf16 v[98:101], v[212:215], v[180:183], v[98:101]
	v_mfma_f32_16x16x32_bf16 v[86:89], v[204:207], v[188:191], v[86:89]
	v_mfma_f32_16x16x32_bf16 v[82:85], v[212:215], v[188:191], v[82:85]
	v_mfma_f32_16x16x32_bf16 v[70:73], v[204:207], v[196:199], v[70:73]
	v_mfma_f32_16x16x32_bf16 v[66:69], v[212:215], v[196:199], v[66:69]
	v_mfma_f32_16x16x32_bf16 v[118:121], v[208:211], v[176:179], v[118:121]
	v_mfma_f32_16x16x32_bf16 v[114:117], v[216:219], v[176:179], v[114:117]
	v_mfma_f32_16x16x32_bf16 v[102:105], v[208:211], v[184:187], v[102:105]
	v_mfma_f32_16x16x32_bf16 v[98:101], v[216:219], v[184:187], v[98:101]
	v_mfma_f32_16x16x32_bf16 v[86:89], v[208:211], v[192:195], v[86:89]
	v_mfma_f32_16x16x32_bf16 v[82:85], v[216:219], v[192:195], v[82:85]
	v_mfma_f32_16x16x32_bf16 v[70:73], v[208:211], v[200:203], v[70:73]
	v_mfma_f32_16x16x32_bf16 v[66:69], v[216:219], v[200:203], v[66:69]
	s_setprio 0
	s_mov_b32 m0, s1
	v_lshl_add_u64 v[222:223], s[26:27], 0, v[130:131]
	s_barrier
	ds_read_b128 v[172:175], v168 offset:16384
	ds_read_b128 v[176:179], v168 offset:17408
	ds_read_b128 v[180:183], v168 offset:18432
	ds_read_b128 v[184:187], v168 offset:19456
	ds_read_b128 v[188:191], v168 offset:20480
	ds_read_b128 v[192:195], v168 offset:21504
	ds_read_b128 v[196:199], v168 offset:22528
	ds_read_b128 v[200:203], v168 offset:23552
	global_load_lds_dwordx4 v[222:223], off
	v_lshl_add_u64 v[224:225], s[26:27], 0, v[132:133]
	s_mov_b32 m0, s35
	s_nop 0
	global_load_lds_dwordx4 v[224:225], off
	s_barrier
	s_waitcnt lgkmcnt(0)
	s_setprio 1
	s_waitcnt lgkmcnt(0)
	v_mfma_f32_16x16x32_bf16 v[62:65], v[144:147], v[172:175], v[62:65]
	v_mfma_f32_16x16x32_bf16 v[58:61], v[152:155], v[172:175], v[58:61]
	v_mfma_f32_16x16x32_bf16 v[46:49], v[144:147], v[180:183], v[46:49]
	v_mfma_f32_16x16x32_bf16 v[42:45], v[152:155], v[180:183], v[42:45]
	v_mfma_f32_16x16x32_bf16 v[30:33], v[144:147], v[188:191], v[30:33]
	v_mfma_f32_16x16x32_bf16 v[26:29], v[152:155], v[188:191], v[26:29]
	v_mfma_f32_16x16x32_bf16 v[14:17], v[144:147], v[196:199], v[14:17]
	v_mfma_f32_16x16x32_bf16 v[10:13], v[152:155], v[196:199], v[10:13]
	v_mfma_f32_16x16x32_bf16 v[62:65], v[148:151], v[176:179], v[62:65]
	v_mfma_f32_16x16x32_bf16 v[58:61], v[156:159], v[176:179], v[58:61]
	v_mfma_f32_16x16x32_bf16 v[46:49], v[148:151], v[184:187], v[46:49]
	v_mfma_f32_16x16x32_bf16 v[42:45], v[156:159], v[184:187], v[42:45]
	v_mfma_f32_16x16x32_bf16 v[30:33], v[148:151], v[192:195], v[30:33]
	v_mfma_f32_16x16x32_bf16 v[26:29], v[156:159], v[192:195], v[26:29]
	v_mfma_f32_16x16x32_bf16 v[14:17], v[148:151], v[200:203], v[14:17]
	v_mfma_f32_16x16x32_bf16 v[10:13], v[156:159], v[200:203], v[10:13]
	s_setprio 0
	s_barrier
	s_add_u32 s52, s24, 0x40000
	s_addc_u32 s53, s25, 0
	s_add_i32 s54, s46, s34
	v_lshl_add_u64 v[144:145], s[52:53], 0, v[130:131]
	s_mov_b32 m0, s54
	s_nop 0
	global_load_lds_dwordx4 v[144:145], off
	v_lshl_add_u64 v[144:145], s[52:53], 0, v[132:133]
	s_add_i32 m0, s54, 0x2000
	s_nop 0
	global_load_lds_dwordx4 v[144:145], off
	s_waitcnt vmcnt(6)
	s_barrier
	s_setprio 1
	v_mfma_f32_16x16x32_bf16 v[54:57], v[204:207], v[172:175], v[54:57]
	v_mfma_f32_16x16x32_bf16 v[50:53], v[212:215], v[172:175], v[50:53]
	v_mfma_f32_16x16x32_bf16 v[38:41], v[204:207], v[180:183], v[38:41]
	v_mfma_f32_16x16x32_bf16 v[34:37], v[212:215], v[180:183], v[34:37]
	v_mfma_f32_16x16x32_bf16 v[22:25], v[204:207], v[188:191], v[22:25]
	v_mfma_f32_16x16x32_bf16 v[18:21], v[212:215], v[188:191], v[18:21]
	v_mfma_f32_16x16x32_bf16 v[6:9], v[204:207], v[196:199], v[6:9]
	v_mfma_f32_16x16x32_bf16 v[2:5], v[212:215], v[196:199], v[2:5]
	v_mfma_f32_16x16x32_bf16 v[54:57], v[208:211], v[176:179], v[54:57]
	v_mfma_f32_16x16x32_bf16 v[50:53], v[216:219], v[176:179], v[50:53]
	v_mfma_f32_16x16x32_bf16 v[38:41], v[208:211], v[184:187], v[38:41]
	v_mfma_f32_16x16x32_bf16 v[34:37], v[216:219], v[184:187], v[34:37]
	v_mfma_f32_16x16x32_bf16 v[22:25], v[208:211], v[192:195], v[22:25]
	v_mfma_f32_16x16x32_bf16 v[18:21], v[216:219], v[192:195], v[18:21]
	v_mfma_f32_16x16x32_bf16 v[6:9], v[208:211], v[200:203], v[6:9]
	v_mfma_f32_16x16x32_bf16 v[2:5], v[216:219], v[200:203], v[2:5]
	s_setprio 0
	s_add_i32 s52, 0, 0x18000
	v_add_u32_e32 v134, s52, v164
	s_barrier
	ds_read_b128 v[144:147], v134
	ds_read_b128 v[148:151], v134 offset:1024
	ds_read_b128 v[152:155], v134 offset:2048
	ds_read_b128 v[156:159], v134 offset:3072
	s_add_u32 s26, s26, 0x40000
	s_addc_u32 s27, s27, 0
	s_mov_b32 m0, s36
	v_lshl_add_u64 v[204:205], s[26:27], 0, v[130:131]
	ds_read_b128 v[172:175], v168 offset:32768
	ds_read_b128 v[176:179], v168 offset:33792
	ds_read_b128 v[180:183], v168 offset:34816
	ds_read_b128 v[184:187], v168 offset:35840
	ds_read_b128 v[188:191], v168 offset:36864
	ds_read_b128 v[192:195], v168 offset:37888
	ds_read_b128 v[196:199], v168 offset:38912
	ds_read_b128 v[200:203], v168 offset:39936
	global_load_lds_dwordx4 v[204:205], off
	v_lshl_add_u64 v[204:205], s[26:27], 0, v[132:133]
	s_mov_b32 m0, s37
	s_nop 0
	global_load_lds_dwordx4 v[204:205], off
	s_waitcnt lgkmcnt(8)
	s_barrier
	s_waitcnt lgkmcnt(0)
	s_setprio 1
	s_waitcnt lgkmcnt(0)
	v_mfma_f32_16x16x32_bf16 v[126:129], v[144:147], v[172:175], v[126:129]
	v_mfma_f32_16x16x32_bf16 v[122:125], v[152:155], v[172:175], v[122:125]
	v_mfma_f32_16x16x32_bf16 v[110:113], v[144:147], v[180:183], v[110:113]
	v_mfma_f32_16x16x32_bf16 v[106:109], v[152:155], v[180:183], v[106:109]
	v_mfma_f32_16x16x32_bf16 v[94:97], v[144:147], v[188:191], v[94:97]
	v_mfma_f32_16x16x32_bf16 v[90:93], v[152:155], v[188:191], v[90:93]
	v_mfma_f32_16x16x32_bf16 v[78:81], v[144:147], v[196:199], v[78:81]
	v_mfma_f32_16x16x32_bf16 v[74:77], v[152:155], v[196:199], v[74:77]
	v_mfma_f32_16x16x32_bf16 v[126:129], v[148:151], v[176:179], v[126:129]
	v_mfma_f32_16x16x32_bf16 v[122:125], v[156:159], v[176:179], v[122:125]
	v_mfma_f32_16x16x32_bf16 v[110:113], v[148:151], v[184:187], v[110:113]
	v_mfma_f32_16x16x32_bf16 v[106:109], v[156:159], v[184:187], v[106:109]
	v_mfma_f32_16x16x32_bf16 v[94:97], v[148:151], v[192:195], v[94:97]
	v_mfma_f32_16x16x32_bf16 v[90:93], v[156:159], v[192:195], v[90:93]
	v_mfma_f32_16x16x32_bf16 v[78:81], v[148:151], v[200:203], v[78:81]
	v_mfma_f32_16x16x32_bf16 v[74:77], v[156:159], v[200:203], v[74:77]
	s_setprio 0
	s_barrier
	s_add_i32 s26, 0, 0x1c000
	s_add_i32 s27, s52, s34
	v_add_u32_e32 v134, s26, v164
	v_lshl_add_u64 v[160:161], v[160:161], 0, s[2:3]
	s_mov_b32 m0, s27
	ds_read_b128 v[204:207], v134
	ds_read_b128 v[208:211], v134 offset:1024
	ds_read_b128 v[212:215], v134 offset:2048
	ds_read_b128 v[216:219], v134 offset:3072
	global_load_lds_dwordx4 v[160:161], off
	v_lshl_add_u64 v[160:161], v[220:221], 0, s[2:3]
	s_add_i32 m0, s27, 0x2000
	s_nop 0
	global_load_lds_dwordx4 v[160:161], off
	s_barrier
	s_waitcnt lgkmcnt(0)
	s_setprio 1
	s_waitcnt lgkmcnt(0)
	v_mfma_f32_16x16x32_bf16 v[118:121], v[204:207], v[172:175], v[118:121]
	v_mfma_f32_16x16x32_bf16 v[114:117], v[212:215], v[172:175], v[114:117]
	v_mfma_f32_16x16x32_bf16 v[102:105], v[204:207], v[180:183], v[102:105]
	v_mfma_f32_16x16x32_bf16 v[98:101], v[212:215], v[180:183], v[98:101]
	v_mfma_f32_16x16x32_bf16 v[86:89], v[204:207], v[188:191], v[86:89]
	v_mfma_f32_16x16x32_bf16 v[82:85], v[212:215], v[188:191], v[82:85]
	v_mfma_f32_16x16x32_bf16 v[70:73], v[204:207], v[196:199], v[70:73]
	v_mfma_f32_16x16x32_bf16 v[66:69], v[212:215], v[196:199], v[66:69]
	v_mfma_f32_16x16x32_bf16 v[118:121], v[208:211], v[176:179], v[118:121]
	v_mfma_f32_16x16x32_bf16 v[114:117], v[216:219], v[176:179], v[114:117]
	v_mfma_f32_16x16x32_bf16 v[102:105], v[208:211], v[184:187], v[102:105]
	v_mfma_f32_16x16x32_bf16 v[98:101], v[216:219], v[184:187], v[98:101]
	v_mfma_f32_16x16x32_bf16 v[86:89], v[208:211], v[192:195], v[86:89]
	v_mfma_f32_16x16x32_bf16 v[82:85], v[216:219], v[192:195], v[82:85]
	v_mfma_f32_16x16x32_bf16 v[70:73], v[208:211], v[200:203], v[70:73]
	v_mfma_f32_16x16x32_bf16 v[66:69], v[216:219], v[200:203], v[66:69]
	s_setprio 0
	s_mov_b32 m0, s41
	v_lshl_add_u64 v[160:161], v[222:223], 0, s[2:3]
	s_barrier
	ds_read_b128 v[172:175], v168 offset:49152
	ds_read_b128 v[176:179], v168 offset:50176
	ds_read_b128 v[180:183], v168 offset:51200
	ds_read_b128 v[184:187], v168 offset:52224
	ds_read_b128 v[188:191], v168 offset:53248
	ds_read_b128 v[192:195], v168 offset:54272
	ds_read_b128 v[196:199], v168 offset:55296
	ds_read_b128 v[200:203], v168 offset:56320
	global_load_lds_dwordx4 v[160:161], off
	v_lshl_add_u64 v[160:161], v[224:225], 0, s[2:3]
	s_mov_b32 m0, s42
	s_nop 0
	global_load_lds_dwordx4 v[160:161], off
	s_barrier
	s_waitcnt lgkmcnt(0)
	s_setprio 1
	s_waitcnt lgkmcnt(0)
	v_mfma_f32_16x16x32_bf16 v[62:65], v[144:147], v[172:175], v[62:65]
	v_mfma_f32_16x16x32_bf16 v[58:61], v[152:155], v[172:175], v[58:61]
	v_mfma_f32_16x16x32_bf16 v[46:49], v[144:147], v[180:183], v[46:49]
	v_mfma_f32_16x16x32_bf16 v[42:45], v[152:155], v[180:183], v[42:45]
	v_mfma_f32_16x16x32_bf16 v[30:33], v[144:147], v[188:191], v[30:33]
	v_mfma_f32_16x16x32_bf16 v[26:29], v[152:155], v[188:191], v[26:29]
	v_mfma_f32_16x16x32_bf16 v[14:17], v[144:147], v[196:199], v[14:17]
	v_mfma_f32_16x16x32_bf16 v[10:13], v[152:155], v[196:199], v[10:13]
	v_mfma_f32_16x16x32_bf16 v[62:65], v[148:151], v[176:179], v[62:65]
	v_mfma_f32_16x16x32_bf16 v[58:61], v[156:159], v[176:179], v[58:61]
	v_mfma_f32_16x16x32_bf16 v[46:49], v[148:151], v[184:187], v[46:49]
	v_mfma_f32_16x16x32_bf16 v[42:45], v[156:159], v[184:187], v[42:45]
	v_mfma_f32_16x16x32_bf16 v[30:33], v[148:151], v[192:195], v[30:33]
	v_mfma_f32_16x16x32_bf16 v[26:29], v[156:159], v[192:195], v[26:29]
	v_mfma_f32_16x16x32_bf16 v[14:17], v[148:151], v[200:203], v[14:17]
	v_mfma_f32_16x16x32_bf16 v[10:13], v[156:159], v[200:203], v[10:13]
	s_setprio 0
	s_barrier
	s_add_u32 s24, s24, 0x40080
	s_addc_u32 s25, s25, 0
	s_add_i32 s26, s26, s34
	v_lshl_add_u64 v[144:145], s[24:25], 0, v[130:131]
	s_mov_b32 m0, s26
	s_nop 0
	global_load_lds_dwordx4 v[144:145], off
	v_lshl_add_u64 v[144:145], s[24:25], 0, v[132:133]
	s_add_i32 m0, s26, 0x2000
	s_nop 0
	global_load_lds_dwordx4 v[144:145], off
	s_waitcnt vmcnt(6)
	s_barrier
	s_setprio 1
	v_mfma_f32_16x16x32_bf16 v[54:57], v[204:207], v[172:175], v[54:57]
	v_mfma_f32_16x16x32_bf16 v[50:53], v[212:215], v[172:175], v[50:53]
	v_mfma_f32_16x16x32_bf16 v[38:41], v[204:207], v[180:183], v[38:41]
	v_mfma_f32_16x16x32_bf16 v[34:37], v[212:215], v[180:183], v[34:37]
	v_mfma_f32_16x16x32_bf16 v[22:25], v[204:207], v[188:191], v[22:25]
	v_mfma_f32_16x16x32_bf16 v[18:21], v[212:215], v[188:191], v[18:21]
	v_mfma_f32_16x16x32_bf16 v[6:9], v[204:207], v[196:199], v[6:9]
	v_mfma_f32_16x16x32_bf16 v[2:5], v[212:215], v[196:199], v[2:5]
	v_mfma_f32_16x16x32_bf16 v[54:57], v[208:211], v[176:179], v[54:57]
	v_mfma_f32_16x16x32_bf16 v[50:53], v[216:219], v[176:179], v[50:53]
	v_mfma_f32_16x16x32_bf16 v[38:41], v[208:211], v[184:187], v[38:41]
	v_mfma_f32_16x16x32_bf16 v[34:37], v[216:219], v[184:187], v[34:37]
	v_mfma_f32_16x16x32_bf16 v[22:25], v[208:211], v[192:195], v[22:25]
	v_mfma_f32_16x16x32_bf16 v[18:21], v[216:219], v[192:195], v[18:21]
	v_mfma_f32_16x16x32_bf16 v[6:9], v[208:211], v[200:203], v[6:9]
	v_mfma_f32_16x16x32_bf16 v[2:5], v[216:219], v[200:203], v[2:5]
	s_setprio 0
	s_add_i32 s51, s51, 2
	s_add_u32 s22, s22, 0x100
	s_addc_u32 s23, s23, 0
	s_add_u32 s29, s29, 0x100
	s_addc_u32 s50, s50, 0
	s_cmp_gt_u32 s51, 13
	s_barrier
	s_cbranch_scc0 .LBB0_474
	s_mov_b64 s[22:23], exec
	s_load_dwordx8 s[52:59], s[78:79], 0x220
	s_load_dwordx4 s[24:27], s[78:79], 0x240
	v_and_b32_e32 v144, 15, v248
	v_bfe_u32 v147, v248, 8, 1
	v_bfe_u32 v145, v248, 6, 2
	v_bfe_u32 v134, v248, 4, 2
	v_lshlrev_b32_e32 v145, 5, v145
	v_lshl_or_b32 v145, v134, 2, v145
	v_lshl_add_u32 v147, v147, 6, v144
	s_lshl_b32 s9, s6, 8
	v_add_u32_e32 v146, s9, v147
	s_cmp_lt_u32 s0, 4
	s_cbranch_scc1 .Lmy_ri_q
	s_cmp_lt_u32 s0, 8
	s_cbranch_scc1 .Lmy_ri_k
	s_cmp_lt_u32 s0, 16
	s_cbranch_scc1 .Lmy_ri_v
	s_branch .Lmy_ri_g
.Lmy_ri_q:
	s_mov_b32 s9, s0
	s_mov_b32 s17, 0xbd3b9ca6
	s_cmp_eq_u32 s9, 1
	s_cselect_b32 s17, 0xbcba1f74, s17
	s_cmp_eq_u32 s9, 2
	s_cselect_b32 s17, 0xbc3963dd, s17
	s_cmp_eq_u32 s9, 3
	s_cselect_b32 s17, 0xbbb906ce, s17
	s_cmp_lt_u32 s6, 64
	s_cbranch_scc0 .Lmy_ri_q_fs
	v_mov_b32_e32 v156, v147
	v_add_u32_e32 v157, 16, v147
	v_add_u32_e32 v158, 32, v147
	v_add_u32_e32 v159, 48, v147
	v_cvt_f32_u32_e32 v156, v156
	v_cvt_f32_u32_e32 v157, v157
	v_cvt_f32_u32_e32 v158, v158
	v_cvt_f32_u32_e32 v159, v159
	v_mul_f32_e32 v156, s17, v156
	v_mul_f32_e32 v157, s17, v157
	v_mul_f32_e32 v158, s17, v158
	v_mul_f32_e32 v159, s17, v159
	v_exp_f32_e32 v148, v156
	v_exp_f32_e32 v150, v157
	v_exp_f32_e32 v152, v158
	v_exp_f32_e32 v154, v159
	s_branch .Lmy_ri_q_fd
.Lmy_ri_q_fs:
	v_and_b32_e32 v156, 7, v144
	v_cvt_f32_u32_e32 v156, v156
	v_mul_f32_e32 v156, s17, v156
	v_exp_f32_e32 v148, v156
	s_nop 1
	v_mov_b32_e32 v150, v148
	v_mov_b32_e32 v152, v148
	v_mov_b32_e32 v154, v148
.Lmy_ri_q_fd:
	s_nop 1
	s_lshl_b32 s9, s0, 9
	v_lshlrev_b32_e32 v149, 11, v146
	v_lshl_add_u32 v149, v145, 1, v149
	v_add_u32_e32 v149, s9, v149
	s_waitcnt lgkmcnt(0)
	v_pk_mul_f32 v[156:157], v[126:127], v[148:149] op_sel_hi:[1,0]
	v_pk_mul_f32 v[158:159], v[128:129], v[148:149] op_sel_hi:[1,0]
	v_cvt_pk_bf16_f32 v160, v156, v157
	v_cvt_pk_bf16_f32 v161, v158, v159
	global_store_dwordx2 v149, v[160:161], s[52:53]
	v_pk_mul_f32 v[156:157], v[122:123], v[148:149] op_sel_hi:[1,0]
	v_pk_mul_f32 v[158:159], v[124:125], v[148:149] op_sel_hi:[1,0]
	v_cvt_pk_bf16_f32 v160, v156, v157
	v_cvt_pk_bf16_f32 v161, v158, v159
	v_add_u32_e32 v134, 0x20, v149
	global_store_dwordx2 v134, v[160:161], s[52:53]
	v_pk_mul_f32 v[156:157], v[118:119], v[148:149] op_sel_hi:[1,0]
	v_pk_mul_f32 v[158:159], v[120:121], v[148:149] op_sel_hi:[1,0]
	v_cvt_pk_bf16_f32 v160, v156, v157
	v_cvt_pk_bf16_f32 v161, v158, v159
	v_add_u32_e32 v134, 0x100, v149
	global_store_dwordx2 v134, v[160:161], s[52:53]
	v_pk_mul_f32 v[156:157], v[114:115], v[148:149] op_sel_hi:[1,0]
	v_pk_mul_f32 v[158:159], v[116:117], v[148:149] op_sel_hi:[1,0]
	v_cvt_pk_bf16_f32 v160, v156, v157
	v_cvt_pk_bf16_f32 v161, v158, v159
	v_add_u32_e32 v134, 0x120, v149
	global_store_dwordx2 v134, v[160:161], s[52:53]
	v_pk_mul_f32 v[156:157], v[110:111], v[150:151] op_sel_hi:[1,0]
	v_pk_mul_f32 v[158:159], v[112:113], v[150:151] op_sel_hi:[1,0]
	v_cvt_pk_bf16_f32 v160, v156, v157
	v_cvt_pk_bf16_f32 v161, v158, v159
	v_add_u32_e32 v134, 0x8000, v149
	global_store_dwordx2 v134, v[160:161], s[52:53]
	v_pk_mul_f32 v[156:157], v[106:107], v[150:151] op_sel_hi:[1,0]
	v_pk_mul_f32 v[158:159], v[108:109], v[150:151] op_sel_hi:[1,0]
	v_cvt_pk_bf16_f32 v160, v156, v157
	v_cvt_pk_bf16_f32 v161, v158, v159
	v_add_u32_e32 v134, 0x8020, v149
	global_store_dwordx2 v134, v[160:161], s[52:53]
	v_pk_mul_f32 v[156:157], v[102:103], v[150:151] op_sel_hi:[1,0]
	v_pk_mul_f32 v[158:159], v[104:105], v[150:151] op_sel_hi:[1,0]
	v_cvt_pk_bf16_f32 v160, v156, v157
	v_cvt_pk_bf16_f32 v161, v158, v159
	v_add_u32_e32 v134, 0x8100, v149
	global_store_dwordx2 v134, v[160:161], s[52:53]
	v_pk_mul_f32 v[156:157], v[98:99], v[150:151] op_sel_hi:[1,0]
	v_pk_mul_f32 v[158:159], v[100:101], v[150:151] op_sel_hi:[1,0]
	v_cvt_pk_bf16_f32 v160, v156, v157
	v_cvt_pk_bf16_f32 v161, v158, v159
	v_add_u32_e32 v134, 0x8120, v149
	global_store_dwordx2 v134, v[160:161], s[52:53]
	v_pk_mul_f32 v[156:157], v[94:95], v[152:153] op_sel_hi:[1,0]
	v_pk_mul_f32 v[158:159], v[96:97], v[152:153] op_sel_hi:[1,0]
	v_cvt_pk_bf16_f32 v160, v156, v157
	v_cvt_pk_bf16_f32 v161, v158, v159
	v_add_u32_e32 v134, 0x10000, v149
	global_store_dwordx2 v134, v[160:161], s[52:53]
	v_pk_mul_f32 v[156:157], v[90:91], v[152:153] op_sel_hi:[1,0]
	v_pk_mul_f32 v[158:159], v[92:93], v[152:153] op_sel_hi:[1,0]
	v_cvt_pk_bf16_f32 v160, v156, v157
	v_cvt_pk_bf16_f32 v161, v158, v159
	v_add_u32_e32 v134, 0x10020, v149
	global_store_dwordx2 v134, v[160:161], s[52:53]
	v_pk_mul_f32 v[156:157], v[86:87], v[152:153] op_sel_hi:[1,0]
	v_pk_mul_f32 v[158:159], v[88:89], v[152:153] op_sel_hi:[1,0]
	v_cvt_pk_bf16_f32 v160, v156, v157
	v_cvt_pk_bf16_f32 v161, v158, v159
	v_add_u32_e32 v134, 0x10100, v149
	global_store_dwordx2 v134, v[160:161], s[52:53]
	v_pk_mul_f32 v[156:157], v[82:83], v[152:153] op_sel_hi:[1,0]
	v_pk_mul_f32 v[158:159], v[84:85], v[152:153] op_sel_hi:[1,0]
	v_cvt_pk_bf16_f32 v160, v156, v157
	v_cvt_pk_bf16_f32 v161, v158, v159
	v_add_u32_e32 v134, 0x10120, v149
	global_store_dwordx2 v134, v[160:161], s[52:53]
	v_pk_mul_f32 v[156:157], v[78:79], v[154:155] op_sel_hi:[1,0]
	v_pk_mul_f32 v[158:159], v[80:81], v[154:155] op_sel_hi:[1,0]
	v_cvt_pk_bf16_f32 v160, v156, v157
	v_cvt_pk_bf16_f32 v161, v158, v159
	v_add_u32_e32 v134, 0x18000, v149
	global_store_dwordx2 v134, v[160:161], s[52:53]
	v_pk_mul_f32 v[156:157], v[74:75], v[154:155] op_sel_hi:[1,0]
	v_pk_mul_f32 v[158:159], v[76:77], v[154:155] op_sel_hi:[1,0]
	v_cvt_pk_bf16_f32 v160, v156, v157
	v_cvt_pk_bf16_f32 v161, v158, v159
	v_add_u32_e32 v134, 0x18020, v149
	global_store_dwordx2 v134, v[160:161], s[52:53]
	v_pk_mul_f32 v[156:157], v[70:71], v[154:155] op_sel_hi:[1,0]
	v_pk_mul_f32 v[158:159], v[72:73], v[154:155] op_sel_hi:[1,0]
	v_cvt_pk_bf16_f32 v160, v156, v157
	v_cvt_pk_bf16_f32 v161, v158, v159
	v_add_u32_e32 v134, 0x18100, v149
	global_store_dwordx2 v134, v[160:161], s[52:53]
	v_pk_mul_f32 v[156:157], v[66:67], v[154:155] op_sel_hi:[1,0]
	v_pk_mul_f32 v[158:159], v[68:69], v[154:155] op_sel_hi:[1,0]
	v_cvt_pk_bf16_f32 v160, v156, v157
	v_cvt_pk_bf16_f32 v161, v158, v159
	v_add_u32_e32 v134, 0x18120, v149
	global_store_dwordx2 v134, v[160:161], s[52:53]
	v_pk_mul_f32 v[156:157], v[62:63], v[148:149] op_sel_hi:[1,0]
	v_pk_mul_f32 v[158:159], v[64:65], v[148:149] op_sel_hi:[1,0]
	v_cvt_pk_bf16_f32 v160, v156, v157
	v_cvt_pk_bf16_f32 v161, v158, v159
	v_add_u32_e32 v134, 0x40000, v149
	global_store_dwordx2 v134, v[160:161], s[52:53]
	v_pk_mul_f32 v[156:157], v[58:59], v[148:149] op_sel_hi:[1,0]
	v_pk_mul_f32 v[158:159], v[60:61], v[148:149] op_sel_hi:[1,0]
	v_cvt_pk_bf16_f32 v160, v156, v157
	v_cvt_pk_bf16_f32 v161, v158, v159
	v_add_u32_e32 v134, 0x40020, v149
	global_store_dwordx2 v134, v[160:161], s[52:53]
	v_pk_mul_f32 v[156:157], v[54:55], v[148:149] op_sel_hi:[1,0]
	v_pk_mul_f32 v[158:159], v[56:57], v[148:149] op_sel_hi:[1,0]
	v_cvt_pk_bf16_f32 v160, v156, v157
	v_cvt_pk_bf16_f32 v161, v158, v159
	v_add_u32_e32 v134, 0x40100, v149
	global_store_dwordx2 v134, v[160:161], s[52:53]
	v_pk_mul_f32 v[156:157], v[50:51], v[148:149] op_sel_hi:[1,0]
	v_pk_mul_f32 v[158:159], v[52:53], v[148:149] op_sel_hi:[1,0]
	v_cvt_pk_bf16_f32 v160, v156, v157
	v_cvt_pk_bf16_f32 v161, v158, v159
	v_add_u32_e32 v134, 0x40120, v149
	global_store_dwordx2 v134, v[160:161], s[52:53]
	v_pk_mul_f32 v[156:157], v[46:47], v[150:151] op_sel_hi:[1,0]
	v_pk_mul_f32 v[158:159], v[48:49], v[150:151] op_sel_hi:[1,0]
	v_cvt_pk_bf16_f32 v160, v156, v157
	v_cvt_pk_bf16_f32 v161, v158, v159
	v_add_u32_e32 v134, 0x48000, v149
	global_store_dwordx2 v134, v[160:161], s[52:53]
	v_pk_mul_f32 v[156:157], v[42:43], v[150:151] op_sel_hi:[1,0]
	v_pk_mul_f32 v[158:159], v[44:45], v[150:151] op_sel_hi:[1,0]
	v_cvt_pk_bf16_f32 v160, v156, v157
	v_cvt_pk_bf16_f32 v161, v158, v159
	v_add_u32_e32 v134, 0x48020, v149
	global_store_dwordx2 v134, v[160:161], s[52:53]
	v_pk_mul_f32 v[156:157], v[38:39], v[150:151] op_sel_hi:[1,0]
	v_pk_mul_f32 v[158:159], v[40:41], v[150:151] op_sel_hi:[1,0]
	v_cvt_pk_bf16_f32 v160, v156, v157
	v_cvt_pk_bf16_f32 v161, v158, v159
	v_add_u32_e32 v134, 0x48100, v149
	global_store_dwordx2 v134, v[160:161], s[52:53]
	v_pk_mul_f32 v[156:157], v[34:35], v[150:151] op_sel_hi:[1,0]
	v_pk_mul_f32 v[158:159], v[36:37], v[150:151] op_sel_hi:[1,0]
	v_cvt_pk_bf16_f32 v160, v156, v157
	v_cvt_pk_bf16_f32 v161, v158, v159
	v_add_u32_e32 v134, 0x48120, v149
	global_store_dwordx2 v134, v[160:161], s[52:53]
	v_pk_mul_f32 v[156:157], v[30:31], v[152:153] op_sel_hi:[1,0]
	v_pk_mul_f32 v[158:159], v[32:33], v[152:153] op_sel_hi:[1,0]
	v_cvt_pk_bf16_f32 v160, v156, v157
	v_cvt_pk_bf16_f32 v161, v158, v159
	v_add_u32_e32 v134, 0x50000, v149
	global_store_dwordx2 v134, v[160:161], s[52:53]
	v_pk_mul_f32 v[156:157], v[26:27], v[152:153] op_sel_hi:[1,0]
	v_pk_mul_f32 v[158:159], v[28:29], v[152:153] op_sel_hi:[1,0]
	v_cvt_pk_bf16_f32 v160, v156, v157
	v_cvt_pk_bf16_f32 v161, v158, v159
	v_add_u32_e32 v134, 0x50020, v149
	global_store_dwordx2 v134, v[160:161], s[52:53]
	v_pk_mul_f32 v[156:157], v[22:23], v[152:153] op_sel_hi:[1,0]
	v_pk_mul_f32 v[158:159], v[24:25], v[152:153] op_sel_hi:[1,0]
	v_cvt_pk_bf16_f32 v160, v156, v157
	v_cvt_pk_bf16_f32 v161, v158, v159
	v_add_u32_e32 v134, 0x50100, v149
	global_store_dwordx2 v134, v[160:161], s[52:53]
	v_pk_mul_f32 v[156:157], v[18:19], v[152:153] op_sel_hi:[1,0]
	v_pk_mul_f32 v[158:159], v[20:21], v[152:153] op_sel_hi:[1,0]
	v_cvt_pk_bf16_f32 v160, v156, v157
	v_cvt_pk_bf16_f32 v161, v158, v159
	v_add_u32_e32 v134, 0x50120, v149
	global_store_dwordx2 v134, v[160:161], s[52:53]
	v_pk_mul_f32 v[156:157], v[14:15], v[154:155] op_sel_hi:[1,0]
	v_pk_mul_f32 v[158:159], v[16:17], v[154:155] op_sel_hi:[1,0]
	v_cvt_pk_bf16_f32 v160, v156, v157
	v_cvt_pk_bf16_f32 v161, v158, v159
	v_add_u32_e32 v134, 0x58000, v149
	global_store_dwordx2 v134, v[160:161], s[52:53]
	v_pk_mul_f32 v[156:157], v[10:11], v[154:155] op_sel_hi:[1,0]
	v_pk_mul_f32 v[158:159], v[12:13], v[154:155] op_sel_hi:[1,0]
	v_cvt_pk_bf16_f32 v160, v156, v157
	v_cvt_pk_bf16_f32 v161, v158, v159
	v_add_u32_e32 v134, 0x58020, v149
	global_store_dwordx2 v134, v[160:161], s[52:53]
	v_pk_mul_f32 v[156:157], v[6:7], v[154:155] op_sel_hi:[1,0]
	v_pk_mul_f32 v[158:159], v[8:9], v[154:155] op_sel_hi:[1,0]
	v_cvt_pk_bf16_f32 v160, v156, v157
	v_cvt_pk_bf16_f32 v161, v158, v159
	v_add_u32_e32 v134, 0x58100, v149
	global_store_dwordx2 v134, v[160:161], s[52:53]
	v_pk_mul_f32 v[156:157], v[2:3], v[154:155] op_sel_hi:[1,0]
	v_pk_mul_f32 v[158:159], v[4:5], v[154:155] op_sel_hi:[1,0]
	v_cvt_pk_bf16_f32 v160, v156, v157
	v_cvt_pk_bf16_f32 v161, v158, v159
	v_add_u32_e32 v134, 0x58120, v149
	global_store_dwordx2 v134, v[160:161], s[52:53]
	s_branch .LBB0_470
.Lmy_ri_k:
	s_sub_u32 s9, s0, 4
	s_mov_b32 s17, 0xbd3b9ca6
	s_cmp_eq_u32 s9, 1
	s_cselect_b32 s17, 0xbcba1f74, s17
	s_cmp_eq_u32 s9, 2
	s_cselect_b32 s17, 0xbc3963dd, s17
	s_cmp_eq_u32 s9, 3
	s_cselect_b32 s17, 0xbbb906ce, s17
	s_xor_b32 s17, s17, 0x80000000
	s_cmp_lt_u32 s6, 64
	s_cbranch_scc0 .Lmy_ri_k_fs
	v_mov_b32_e32 v156, v147
	v_add_u32_e32 v157, 16, v147
	v_add_u32_e32 v158, 32, v147
	v_add_u32_e32 v159, 48, v147
	v_cvt_f32_u32_e32 v156, v156
	v_cvt_f32_u32_e32 v157, v157
	v_cvt_f32_u32_e32 v158, v158
	v_cvt_f32_u32_e32 v159, v159
	v_mul_f32_e32 v156, s17, v156
	v_mul_f32_e32 v157, s17, v157
	v_mul_f32_e32 v158, s17, v158
	v_mul_f32_e32 v159, s17, v159
	v_exp_f32_e32 v148, v156
	v_exp_f32_e32 v150, v157
	v_exp_f32_e32 v152, v158
	v_exp_f32_e32 v154, v159
	s_branch .Lmy_ri_k_fd

.Lmy_ri_k_fd:
	s_nop 1
	s_sub_u32 s9, s0, 4
	s_lshl_b32 s17, s9, 9
	v_lshlrev_b32_e32 v149, 11, v146
	v_lshl_add_u32 v149, v145, 1, v149
	v_add_u32_e32 v149, s17, v149
	s_cmp_lt_u32 s6, 64
	s_cbranch_scc0 .Lmy_ri_ks
	s_lshr_b32 s17, s6, 3
	s_lshl_b32 s17, s17, 2
	s_add_u32 s9, s9, s17
	s_lshl_b32 s9, s9, 20
	s_and_b32 s17, s6, 7
	s_lshl_b32 s17, s17, 9
	s_add_u32 s9, s9, s17
	v_lshlrev_b32_e32 v151, 12, v145
	v_lshl_add_u32 v151, v147, 1, v151
	v_add_u32_e32 v151, s9, v151
	s_waitcnt lgkmcnt(0)
	s_add_u32 s26, s24, 0x1000
	s_addc_u32 s27, s25, 0
	s_add_u32 s28, s24, 0x2000
	s_addc_u32 s29, s25, 0
	s_add_u32 s6, s24, 0x3000
	s_addc_u32 s7, s25, 0
	v_pk_mul_f32 v[156:157], v[126:127], v[148:149] op_sel_hi:[1,0]
	v_pk_mul_f32 v[158:159], v[128:129], v[148:149] op_sel_hi:[1,0]
	v_cvt_pk_bf16_f32 v160, v156, v157
	v_cvt_pk_bf16_f32 v161, v158, v159
	global_store_dwordx2 v149, v[160:161], s[54:55]
	global_store_short v151, v160, s[24:25]
	global_store_short_d16_hi v151, v160, s[26:27]
	global_store_short v151, v161, s[28:29]
	global_store_short_d16_hi v151, v161, s[6:7]
	v_pk_mul_f32 v[156:157], v[122:123], v[148:149] op_sel_hi:[1,0]
	v_pk_mul_f32 v[158:159], v[124:125], v[148:149] op_sel_hi:[1,0]
	v_cvt_pk_bf16_f32 v160, v156, v157
	v_cvt_pk_bf16_f32 v161, v158, v159
	v_add_u32_e32 v134, 0x20, v149
	global_store_dwordx2 v134, v[160:161], s[54:55]
	v_add_u32_e32 v172, 0x10000, v151
	global_store_short v172, v160, s[24:25]
	global_store_short_d16_hi v172, v160, s[26:27]
	global_store_short v172, v161, s[28:29]
	global_store_short_d16_hi v172, v161, s[6:7]
	v_pk_mul_f32 v[156:157], v[118:119], v[148:149] op_sel_hi:[1,0]
	v_pk_mul_f32 v[158:159], v[120:121], v[148:149] op_sel_hi:[1,0]
	v_cvt_pk_bf16_f32 v160, v156, v157
	v_cvt_pk_bf16_f32 v161, v158, v159
	v_add_u32_e32 v134, 0x100, v149
	global_store_dwordx2 v134, v[160:161], s[54:55]
	v_add_u32_e32 v172, 0x80000, v151
	global_store_short v172, v160, s[24:25]
	global_store_short_d16_hi v172, v160, s[26:27]
	global_store_short v172, v161, s[28:29]
	global_store_short_d16_hi v172, v161, s[6:7]
	v_pk_mul_f32 v[156:157], v[114:115], v[148:149] op_sel_hi:[1,0]
	v_pk_mul_f32 v[158:159], v[116:117], v[148:149] op_sel_hi:[1,0]
	v_cvt_pk_bf16_f32 v160, v156, v157
	v_cvt_pk_bf16_f32 v161, v158, v159
	v_add_u32_e32 v134, 0x120, v149
	global_store_dwordx2 v134, v[160:161], s[54:55]
	v_add_u32_e32 v172, 0x90000, v151
	global_store_short v172, v160, s[24:25]
	global_store_short_d16_hi v172, v160, s[26:27]
	global_store_short v172, v161, s[28:29]
	global_store_short_d16_hi v172, v161, s[6:7]
	v_pk_mul_f32 v[156:157], v[110:111], v[150:151] op_sel_hi:[1,0]
	v_pk_mul_f32 v[158:159], v[112:113], v[150:151] op_sel_hi:[1,0]
	v_cvt_pk_bf16_f32 v160, v156, v157
	v_cvt_pk_bf16_f32 v161, v158, v159
	v_add_u32_e32 v134, 0x8000, v149
	global_store_dwordx2 v134, v[160:161], s[54:55]
	v_add_u32_e32 v172, 0x20, v151
	global_store_short v172, v160, s[24:25]
	global_store_short_d16_hi v172, v160, s[26:27]
	global_store_short v172, v161, s[28:29]
	global_store_short_d16_hi v172, v161, s[6:7]
	v_pk_mul_f32 v[156:157], v[106:107], v[150:151] op_sel_hi:[1,0]
	v_pk_mul_f32 v[158:159], v[108:109], v[150:151] op_sel_hi:[1,0]
	v_cvt_pk_bf16_f32 v160, v156, v157
	v_cvt_pk_bf16_f32 v161, v158, v159
	v_add_u32_e32 v134, 0x8020, v149
	global_store_dwordx2 v134, v[160:161], s[54:55]
	v_add_u32_e32 v172, 0x10020, v151
	global_store_short v172, v160, s[24:25]
	global_store_short_d16_hi v172, v160, s[26:27]
	global_store_short v172, v161, s[28:29]
	global_store_short_d16_hi v172, v161, s[6:7]
	v_pk_mul_f32 v[156:157], v[102:103], v[150:151] op_sel_hi:[1,0]
	v_pk_mul_f32 v[158:159], v[104:105], v[150:151] op_sel_hi:[1,0]
	v_cvt_pk_bf16_f32 v160, v156, v157
	v_cvt_pk_bf16_f32 v161, v158, v159
	v_add_u32_e32 v134, 0x8100, v149
	global_store_dwordx2 v134, v[160:161], s[54:55]
	v_add_u32_e32 v172, 0x80020, v151
	global_store_short v172, v160, s[24:25]
	global_store_short_d16_hi v172, v160, s[26:27]
	global_store_short v172, v161, s[28:29]
	global_store_short_d16_hi v172, v161, s[6:7]
	v_pk_mul_f32 v[156:157], v[98:99], v[150:151] op_sel_hi:[1,0]
	v_pk_mul_f32 v[158:159], v[100:101], v[150:151] op_sel_hi:[1,0]
	v_cvt_pk_bf16_f32 v160, v156, v157
	v_cvt_pk_bf16_f32 v161, v158, v159
	v_add_u32_e32 v134, 0x8120, v149
	global_store_dwordx2 v134, v[160:161], s[54:55]
	v_add_u32_e32 v172, 0x90020, v151
	global_store_short v172, v160, s[24:25]
	global_store_short_d16_hi v172, v160, s[26:27]
	global_store_short v172, v161, s[28:29]
	global_store_short_d16_hi v172, v161, s[6:7]
	v_pk_mul_f32 v[156:157], v[94:95], v[152:153] op_sel_hi:[1,0]
	v_pk_mul_f32 v[158:159], v[96:97], v[152:153] op_sel_hi:[1,0]
	v_cvt_pk_bf16_f32 v160, v156, v157
	v_cvt_pk_bf16_f32 v161, v158, v159
	v_add_u32_e32 v134, 0x10000, v149
	global_store_dwordx2 v134, v[160:161], s[54:55]
	v_add_u32_e32 v172, 0x40, v151
	global_store_short v172, v160, s[24:25]
	global_store_short_d16_hi v172, v160, s[26:27]
	global_store_short v172, v161, s[28:29]
	global_store_short_d16_hi v172, v161, s[6:7]
	v_pk_mul_f32 v[156:157], v[90:91], v[152:153] op_sel_hi:[1,0]
	v_pk_mul_f32 v[158:159], v[92:93], v[152:153] op_sel_hi:[1,0]
	v_cvt_pk_bf16_f32 v160, v156, v157
	v_cvt_pk_bf16_f32 v161, v158, v159
	v_add_u32_e32 v134, 0x10020, v149
	global_store_dwordx2 v134, v[160:161], s[54:55]
	v_add_u32_e32 v172, 0x10040, v151
	global_store_short v172, v160, s[24:25]
	global_store_short_d16_hi v172, v160, s[26:27]
	global_store_short v172, v161, s[28:29]
	global_store_short_d16_hi v172, v161, s[6:7]
	v_pk_mul_f32 v[156:157], v[86:87], v[152:153] op_sel_hi:[1,0]
	v_pk_mul_f32 v[158:159], v[88:89], v[152:153] op_sel_hi:[1,0]
	v_cvt_pk_bf16_f32 v160, v156, v157
	v_cvt_pk_bf16_f32 v161, v158, v159
	v_add_u32_e32 v134, 0x10100, v149
	global_store_dwordx2 v134, v[160:161], s[54:55]
	v_add_u32_e32 v172, 0x80040, v151
	global_store_short v172, v160, s[24:25]
	global_store_short_d16_hi v172, v160, s[26:27]
	global_store_short v172, v161, s[28:29]
	global_store_short_d16_hi v172, v161, s[6:7]
	v_pk_mul_f32 v[156:157], v[82:83], v[152:153] op_sel_hi:[1,0]
	v_pk_mul_f32 v[158:159], v[84:85], v[152:153] op_sel_hi:[1,0]
	v_cvt_pk_bf16_f32 v160, v156, v157
	v_cvt_pk_bf16_f32 v161, v158, v159
	v_add_u32_e32 v134, 0x10120, v149
	global_store_dwordx2 v134, v[160:161], s[54:55]
	v_add_u32_e32 v172, 0x90040, v151
	global_store_short v172, v160, s[24:25]
	global_store_short_d16_hi v172, v160, s[26:27]
	global_store_short v172, v161, s[28:29]
	global_store_short_d16_hi v172, v161, s[6:7]
	v_pk_mul_f32 v[156:157], v[78:79], v[154:155] op_sel_hi:[1,0]
	v_pk_mul_f32 v[158:159], v[80:81], v[154:155] op_sel_hi:[1,0]
	v_cvt_pk_bf16_f32 v160, v156, v157
	v_cvt_pk_bf16_f32 v161, v158, v159
	v_add_u32_e32 v134, 0x18000, v149
	global_store_dwordx2 v134, v[160:161], s[54:55]
	v_add_u32_e32 v172, 0x60, v151
	global_store_short v172, v160, s[24:25]
	global_store_short_d16_hi v172, v160, s[26:27]
	global_store_short v172, v161, s[28:29]
	global_store_short_d16_hi v172, v161, s[6:7]
	v_pk_mul_f32 v[156:157], v[74:75], v[154:155] op_sel_hi:[1,0]
	v_pk_mul_f32 v[158:159], v[76:77], v[154:155] op_sel_hi:[1,0]
	v_cvt_pk_bf16_f32 v160, v156, v157
	v_cvt_pk_bf16_f32 v161, v158, v159
	v_add_u32_e32 v134, 0x18020, v149
	global_store_dwordx2 v134, v[160:161], s[54:55]
	v_add_u32_e32 v172, 0x10060, v151
	global_store_short v172, v160, s[24:25]
	global_store_short_d16_hi v172, v160, s[26:27]
	global_store_short v172, v161, s[28:29]
	global_store_short_d16_hi v172, v161, s[6:7]
	v_pk_mul_f32 v[156:157], v[70:71], v[154:155] op_sel_hi:[1,0]
	v_pk_mul_f32 v[158:159], v[72:73], v[154:155] op_sel_hi:[1,0]
	v_cvt_pk_bf16_f32 v160, v156, v157
	v_cvt_pk_bf16_f32 v161, v158, v159
	v_add_u32_e32 v134, 0x18100, v149
	global_store_dwordx2 v134, v[160:161], s[54:55]
	v_add_u32_e32 v172, 0x80060, v151
	global_store_short v172, v160, s[24:25]
	global_store_short_d16_hi v172, v160, s[26:27]
	global_store_short v172, v161, s[28:29]
	global_store_short_d16_hi v172, v161, s[6:7]
	v_pk_mul_f32 v[156:157], v[66:67], v[154:155] op_sel_hi:[1,0]
	v_pk_mul_f32 v[158:159], v[68:69], v[154:155] op_sel_hi:[1,0]
	v_cvt_pk_bf16_f32 v160, v156, v157
	v_cvt_pk_bf16_f32 v161, v158, v159
	v_add_u32_e32 v134, 0x18120, v149
	global_store_dwordx2 v134, v[160:161], s[54:55]
	v_add_u32_e32 v172, 0x90060, v151
	global_store_short v172, v160, s[24:25]
	global_store_short_d16_hi v172, v160, s[26:27]
	global_store_short v172, v161, s[28:29]
	global_store_short_d16_hi v172, v161, s[6:7]
	v_pk_mul_f32 v[156:157], v[62:63], v[148:149] op_sel_hi:[1,0]
	v_pk_mul_f32 v[158:159], v[64:65], v[148:149] op_sel_hi:[1,0]
	v_cvt_pk_bf16_f32 v160, v156, v157
	v_cvt_pk_bf16_f32 v161, v158, v159
	v_add_u32_e32 v134, 0x40000, v149
	global_store_dwordx2 v134, v[160:161], s[54:55]
	v_add_u32_e32 v172, 0x100, v151
	global_store_short v172, v160, s[24:25]
	global_store_short_d16_hi v172, v160, s[26:27]
	global_store_short v172, v161, s[28:29]
	global_store_short_d16_hi v172, v161, s[6:7]
	v_pk_mul_f32 v[156:157], v[58:59], v[148:149] op_sel_hi:[1,0]
	v_pk_mul_f32 v[158:159], v[60:61], v[148:149] op_sel_hi:[1,0]
	v_cvt_pk_bf16_f32 v160, v156, v157
	v_cvt_pk_bf16_f32 v161, v158, v159
	v_add_u32_e32 v134, 0x40020, v149
	global_store_dwordx2 v134, v[160:161], s[54:55]
	v_add_u32_e32 v172, 0x10100, v151
	global_store_short v172, v160, s[24:25]
	global_store_short_d16_hi v172, v160, s[26:27]
	global_store_short v172, v161, s[28:29]
	global_store_short_d16_hi v172, v161, s[6:7]
	v_pk_mul_f32 v[156:157], v[54:55], v[148:149] op_sel_hi:[1,0]
	v_pk_mul_f32 v[158:159], v[56:57], v[148:149] op_sel_hi:[1,0]
	v_cvt_pk_bf16_f32 v160, v156, v157
	v_cvt_pk_bf16_f32 v161, v158, v159
	v_add_u32_e32 v134, 0x40100, v149
	global_store_dwordx2 v134, v[160:161], s[54:55]
	v_add_u32_e32 v172, 0x80100, v151
	global_store_short v172, v160, s[24:25]
	global_store_short_d16_hi v172, v160, s[26:27]
	global_store_short v172, v161, s[28:29]
	global_store_short_d16_hi v172, v161, s[6:7]
	v_pk_mul_f32 v[156:157], v[50:51], v[148:149] op_sel_hi:[1,0]
	v_pk_mul_f32 v[158:159], v[52:53], v[148:149] op_sel_hi:[1,0]
	v_cvt_pk_bf16_f32 v160, v156, v157
	v_cvt_pk_bf16_f32 v161, v158, v159
	v_add_u32_e32 v134, 0x40120, v149
	global_store_dwordx2 v134, v[160:161], s[54:55]
	v_add_u32_e32 v172, 0x90100, v151
	global_store_short v172, v160, s[24:25]
	global_store_short_d16_hi v172, v160, s[26:27]
	global_store_short v172, v161, s[28:29]
	global_store_short_d16_hi v172, v161, s[6:7]
	v_pk_mul_f32 v[156:157], v[46:47], v[150:151] op_sel_hi:[1,0]
	v_pk_mul_f32 v[158:159], v[48:49], v[150:151] op_sel_hi:[1,0]
	v_cvt_pk_bf16_f32 v160, v156, v157
	v_cvt_pk_bf16_f32 v161, v158, v159
	v_add_u32_e32 v134, 0x48000, v149
	global_store_dwordx2 v134, v[160:161], s[54:55]
	v_add_u32_e32 v172, 0x120, v151
	global_store_short v172, v160, s[24:25]
	global_store_short_d16_hi v172, v160, s[26:27]
	global_store_short v172, v161, s[28:29]
	global_store_short_d16_hi v172, v161, s[6:7]
	v_pk_mul_f32 v[156:157], v[42:43], v[150:151] op_sel_hi:[1,0]
	v_pk_mul_f32 v[158:159], v[44:45], v[150:151] op_sel_hi:[1,0]
	v_cvt_pk_bf16_f32 v160, v156, v157
	v_cvt_pk_bf16_f32 v161, v158, v159
	v_add_u32_e32 v134, 0x48020, v149
	global_store_dwordx2 v134, v[160:161], s[54:55]
	v_add_u32_e32 v172, 0x10120, v151
	global_store_short v172, v160, s[24:25]
	global_store_short_d16_hi v172, v160, s[26:27]
	global_store_short v172, v161, s[28:29]
	global_store_short_d16_hi v172, v161, s[6:7]
	v_pk_mul_f32 v[156:157], v[38:39], v[150:151] op_sel_hi:[1,0]
	v_pk_mul_f32 v[158:159], v[40:41], v[150:151] op_sel_hi:[1,0]
	v_cvt_pk_bf16_f32 v160, v156, v157
	v_cvt_pk_bf16_f32 v161, v158, v159
	v_add_u32_e32 v134, 0x48100, v149
	global_store_dwordx2 v134, v[160:161], s[54:55]
	v_add_u32_e32 v172, 0x80120, v151
	global_store_short v172, v160, s[24:25]
	global_store_short_d16_hi v172, v160, s[26:27]
	global_store_short v172, v161, s[28:29]
	global_store_short_d16_hi v172, v161, s[6:7]
	v_pk_mul_f32 v[156:157], v[34:35], v[150:151] op_sel_hi:[1,0]
	v_pk_mul_f32 v[158:159], v[36:37], v[150:151] op_sel_hi:[1,0]
	v_cvt_pk_bf16_f32 v160, v156, v157
	v_cvt_pk_bf16_f32 v161, v158, v159
	v_add_u32_e32 v134, 0x48120, v149
	global_store_dwordx2 v134, v[160:161], s[54:55]
	v_add_u32_e32 v172, 0x90120, v151
	global_store_short v172, v160, s[24:25]
	global_store_short_d16_hi v172, v160, s[26:27]
	global_store_short v172, v161, s[28:29]
	global_store_short_d16_hi v172, v161, s[6:7]
	v_pk_mul_f32 v[156:157], v[30:31], v[152:153] op_sel_hi:[1,0]
	v_pk_mul_f32 v[158:159], v[32:33], v[152:153] op_sel_hi:[1,0]
	v_cvt_pk_bf16_f32 v160, v156, v157
	v_cvt_pk_bf16_f32 v161, v158, v159
	v_add_u32_e32 v134, 0x50000, v149
	global_store_dwordx2 v134, v[160:161], s[54:55]
	v_add_u32_e32 v172, 0x140, v151
	global_store_short v172, v160, s[24:25]
	global_store_short_d16_hi v172, v160, s[26:27]
	global_store_short v172, v161, s[28:29]
	global_store_short_d16_hi v172, v161, s[6:7]
	v_pk_mul_f32 v[156:157], v[26:27], v[152:153] op_sel_hi:[1,0]
	v_pk_mul_f32 v[158:159], v[28:29], v[152:153] op_sel_hi:[1,0]
	v_cvt_pk_bf16_f32 v160, v156, v157
	v_cvt_pk_bf16_f32 v161, v158, v159
	v_add_u32_e32 v134, 0x50020, v149
	global_store_dwordx2 v134, v[160:161], s[54:55]
	v_add_u32_e32 v172, 0x10140, v151
	global_store_short v172, v160, s[24:25]
	global_store_short_d16_hi v172, v160, s[26:27]
	global_store_short v172, v161, s[28:29]
	global_store_short_d16_hi v172, v161, s[6:7]
	v_pk_mul_f32 v[156:157], v[22:23], v[152:153] op_sel_hi:[1,0]
	v_pk_mul_f32 v[158:159], v[24:25], v[152:153] op_sel_hi:[1,0]
	v_cvt_pk_bf16_f32 v160, v156, v157
	v_cvt_pk_bf16_f32 v161, v158, v159
	v_add_u32_e32 v134, 0x50100, v149
	global_store_dwordx2 v134, v[160:161], s[54:55]
	v_add_u32_e32 v172, 0x80140, v151
	global_store_short v172, v160, s[24:25]
	global_store_short_d16_hi v172, v160, s[26:27]
	global_store_short v172, v161, s[28:29]
	global_store_short_d16_hi v172, v161, s[6:7]
	v_pk_mul_f32 v[156:157], v[18:19], v[152:153] op_sel_hi:[1,0]
	v_pk_mul_f32 v[158:159], v[20:21], v[152:153] op_sel_hi:[1,0]
	v_cvt_pk_bf16_f32 v160, v156, v157
	v_cvt_pk_bf16_f32 v161, v158, v159
	v_add_u32_e32 v134, 0x50120, v149
	global_store_dwordx2 v134, v[160:161], s[54:55]
	v_add_u32_e32 v172, 0x90140, v151
	global_store_short v172, v160, s[24:25]
	global_store_short_d16_hi v172, v160, s[26:27]
	global_store_short v172, v161, s[28:29]
	global_store_short_d16_hi v172, v161, s[6:7]
	v_pk_mul_f32 v[156:157], v[14:15], v[154:155] op_sel_hi:[1,0]
	v_pk_mul_f32 v[158:159], v[16:17], v[154:155] op_sel_hi:[1,0]
	v_cvt_pk_bf16_f32 v160, v156, v157
	v_cvt_pk_bf16_f32 v161, v158, v159
	v_add_u32_e32 v134, 0x58000, v149
	global_store_dwordx2 v134, v[160:161], s[54:55]
	v_add_u32_e32 v172, 0x160, v151
	global_store_short v172, v160, s[24:25]
	global_store_short_d16_hi v172, v160, s[26:27]
	global_store_short v172, v161, s[28:29]
	global_store_short_d16_hi v172, v161, s[6:7]
	v_pk_mul_f32 v[156:157], v[10:11], v[154:155] op_sel_hi:[1,0]
	v_pk_mul_f32 v[158:159], v[12:13], v[154:155] op_sel_hi:[1,0]
	v_cvt_pk_bf16_f32 v160, v156, v157
	v_cvt_pk_bf16_f32 v161, v158, v159
	v_add_u32_e32 v134, 0x58020, v149
	global_store_dwordx2 v134, v[160:161], s[54:55]
	v_add_u32_e32 v172, 0x10160, v151
	global_store_short v172, v160, s[24:25]
	global_store_short_d16_hi v172, v160, s[26:27]
	global_store_short v172, v161, s[28:29]
	global_store_short_d16_hi v172, v161, s[6:7]
	v_pk_mul_f32 v[156:157], v[6:7], v[154:155] op_sel_hi:[1,0]
	v_pk_mul_f32 v[158:159], v[8:9], v[154:155] op_sel_hi:[1,0]
	v_cvt_pk_bf16_f32 v160, v156, v157
	v_cvt_pk_bf16_f32 v161, v158, v159
	v_add_u32_e32 v134, 0x58100, v149
	global_store_dwordx2 v134, v[160:161], s[54:55]
	v_add_u32_e32 v172, 0x80160, v151
	global_store_short v172, v160, s[24:25]
	global_store_short_d16_hi v172, v160, s[26:27]
	global_store_short v172, v161, s[28:29]
	global_store_short_d16_hi v172, v161, s[6:7]
	v_pk_mul_f32 v[156:157], v[2:3], v[154:155] op_sel_hi:[1,0]
	v_pk_mul_f32 v[158:159], v[4:5], v[154:155] op_sel_hi:[1,0]
	v_cvt_pk_bf16_f32 v160, v156, v157
	v_cvt_pk_bf16_f32 v161, v158, v159
	v_add_u32_e32 v134, 0x58120, v149
	global_store_dwordx2 v134, v[160:161], s[54:55]
	v_add_u32_e32 v172, 0x90160, v151
	global_store_short v172, v160, s[24:25]
	global_store_short_d16_hi v172, v160, s[26:27]
	global_store_short v172, v161, s[28:29]
	global_store_short_d16_hi v172, v161, s[6:7]
	s_branch .LBB0_470
.Lmy_ri_ks:
	s_waitcnt lgkmcnt(0)
	v_pk_mul_f32 v[156:157], v[126:127], v[148:149] op_sel_hi:[1,0]
	v_pk_mul_f32 v[158:159], v[128:129], v[148:149] op_sel_hi:[1,0]
	v_cvt_pk_bf16_f32 v160, v156, v157
	v_cvt_pk_bf16_f32 v161, v158, v159
	global_store_dwordx2 v149, v[160:161], s[54:55]
	v_pk_mul_f32 v[156:157], v[122:123], v[148:149] op_sel_hi:[1,0]
	v_pk_mul_f32 v[158:159], v[124:125], v[148:149] op_sel_hi:[1,0]
	v_cvt_pk_bf16_f32 v160, v156, v157
	v_cvt_pk_bf16_f32 v161, v158, v159
	v_add_u32_e32 v134, 0x20, v149
	global_store_dwordx2 v134, v[160:161], s[54:55]
	v_pk_mul_f32 v[156:157], v[118:119], v[148:149] op_sel_hi:[1,0]
	v_pk_mul_f32 v[158:159], v[120:121], v[148:149] op_sel_hi:[1,0]
	v_cvt_pk_bf16_f32 v160, v156, v157
	v_cvt_pk_bf16_f32 v161, v158, v159
	v_add_u32_e32 v134, 0x100, v149
	global_store_dwordx2 v134, v[160:161], s[54:55]
	v_pk_mul_f32 v[156:157], v[114:115], v[148:149] op_sel_hi:[1,0]
	v_pk_mul_f32 v[158:159], v[116:117], v[148:149] op_sel_hi:[1,0]
	v_cvt_pk_bf16_f32 v160, v156, v157
	v_cvt_pk_bf16_f32 v161, v158, v159
	v_add_u32_e32 v134, 0x120, v149
	global_store_dwordx2 v134, v[160:161], s[54:55]
	v_pk_mul_f32 v[156:157], v[110:111], v[150:151] op_sel_hi:[1,0]
	v_pk_mul_f32 v[158:159], v[112:113], v[150:151] op_sel_hi:[1,0]
	v_cvt_pk_bf16_f32 v160, v156, v157
	v_cvt_pk_bf16_f32 v161, v158, v159
	v_add_u32_e32 v134, 0x8000, v149
	global_store_dwordx2 v134, v[160:161], s[54:55]
	v_pk_mul_f32 v[156:157], v[106:107], v[150:151] op_sel_hi:[1,0]
	v_pk_mul_f32 v[158:159], v[108:109], v[150:151] op_sel_hi:[1,0]
	v_cvt_pk_bf16_f32 v160, v156, v157
	v_cvt_pk_bf16_f32 v161, v158, v159
	v_add_u32_e32 v134, 0x8020, v149
	global_store_dwordx2 v134, v[160:161], s[54:55]
	v_pk_mul_f32 v[156:157], v[102:103], v[150:151] op_sel_hi:[1,0]
	v_pk_mul_f32 v[158:159], v[104:105], v[150:151] op_sel_hi:[1,0]
	v_cvt_pk_bf16_f32 v160, v156, v157
	v_cvt_pk_bf16_f32 v161, v158, v159
	v_add_u32_e32 v134, 0x8100, v149
	global_store_dwordx2 v134, v[160:161], s[54:55]
	v_pk_mul_f32 v[156:157], v[98:99], v[150:151] op_sel_hi:[1,0]
	v_pk_mul_f32 v[158:159], v[100:101], v[150:151] op_sel_hi:[1,0]
	v_cvt_pk_bf16_f32 v160, v156, v157
	v_cvt_pk_bf16_f32 v161, v158, v159
	v_add_u32_e32 v134, 0x8120, v149
	global_store_dwordx2 v134, v[160:161], s[54:55]
	v_pk_mul_f32 v[156:157], v[94:95], v[152:153] op_sel_hi:[1,0]
	v_pk_mul_f32 v[158:159], v[96:97], v[152:153] op_sel_hi:[1,0]
	v_cvt_pk_bf16_f32 v160, v156, v157
	v_cvt_pk_bf16_f32 v161, v158, v159
	v_add_u32_e32 v134, 0x10000, v149
	global_store_dwordx2 v134, v[160:161], s[54:55]
	v_pk_mul_f32 v[156:157], v[90:91], v[152:153] op_sel_hi:[1,0]
	v_pk_mul_f32 v[158:159], v[92:93], v[152:153] op_sel_hi:[1,0]
	v_cvt_pk_bf16_f32 v160, v156, v157
	v_cvt_pk_bf16_f32 v161, v158, v159
	v_add_u32_e32 v134, 0x10020, v149
	global_store_dwordx2 v134, v[160:161], s[54:55]
	v_pk_mul_f32 v[156:157], v[86:87], v[152:153] op_sel_hi:[1,0]
	v_pk_mul_f32 v[158:159], v[88:89], v[152:153] op_sel_hi:[1,0]
	v_cvt_pk_bf16_f32 v160, v156, v157
	v_cvt_pk_bf16_f32 v161, v158, v159
	v_add_u32_e32 v134, 0x10100, v149
	global_store_dwordx2 v134, v[160:161], s[54:55]
	v_pk_mul_f32 v[156:157], v[82:83], v[152:153] op_sel_hi:[1,0]
	v_pk_mul_f32 v[158:159], v[84:85], v[152:153] op_sel_hi:[1,0]
	v_cvt_pk_bf16_f32 v160, v156, v157
	v_cvt_pk_bf16_f32 v161, v158, v159
	v_add_u32_e32 v134, 0x10120, v149
	global_store_dwordx2 v134, v[160:161], s[54:55]
	v_pk_mul_f32 v[156:157], v[78:79], v[154:155] op_sel_hi:[1,0]
	v_pk_mul_f32 v[158:159], v[80:81], v[154:155] op_sel_hi:[1,0]
	v_cvt_pk_bf16_f32 v160, v156, v157
	v_cvt_pk_bf16_f32 v161, v158, v159
	v_add_u32_e32 v134, 0x18000, v149
	global_store_dwordx2 v134, v[160:161], s[54:55]
	v_pk_mul_f32 v[156:157], v[74:75], v[154:155] op_sel_hi:[1,0]
	v_pk_mul_f32 v[158:159], v[76:77], v[154:155] op_sel_hi:[1,0]
	v_cvt_pk_bf16_f32 v160, v156, v157
	v_cvt_pk_bf16_f32 v161, v158, v159
	v_add_u32_e32 v134, 0x18020, v149
	global_store_dwordx2 v134, v[160:161], s[54:55]
	v_pk_mul_f32 v[156:157], v[70:71], v[154:155] op_sel_hi:[1,0]
	v_pk_mul_f32 v[158:159], v[72:73], v[154:155] op_sel_hi:[1,0]
	v_cvt_pk_bf16_f32 v160, v156, v157
	v_cvt_pk_bf16_f32 v161, v158, v159
	v_add_u32_e32 v134, 0x18100, v149
	global_store_dwordx2 v134, v[160:161], s[54:55]
	v_pk_mul_f32 v[156:157], v[66:67], v[154:155] op_sel_hi:[1,0]
	v_pk_mul_f32 v[158:159], v[68:69], v[154:155] op_sel_hi:[1,0]
	v_cvt_pk_bf16_f32 v160, v156, v157
	v_cvt_pk_bf16_f32 v161, v158, v159
	v_add_u32_e32 v134, 0x18120, v149
	global_store_dwordx2 v134, v[160:161], s[54:55]
	v_pk_mul_f32 v[156:157], v[62:63], v[148:149] op_sel_hi:[1,0]
	v_pk_mul_f32 v[158:159], v[64:65], v[148:149] op_sel_hi:[1,0]
	v_cvt_pk_bf16_f32 v160, v156, v157
	v_cvt_pk_bf16_f32 v161, v158, v159
	v_add_u32_e32 v134, 0x40000, v149
	global_store_dwordx2 v134, v[160:161], s[54:55]
	v_pk_mul_f32 v[156:157], v[58:59], v[148:149] op_sel_hi:[1,0]
	v_pk_mul_f32 v[158:159], v[60:61], v[148:149] op_sel_hi:[1,0]
	v_cvt_pk_bf16_f32 v160, v156, v157
	v_cvt_pk_bf16_f32 v161, v158, v159
	v_add_u32_e32 v134, 0x40020, v149
	global_store_dwordx2 v134, v[160:161], s[54:55]
	v_pk_mul_f32 v[156:157], v[54:55], v[148:149] op_sel_hi:[1,0]
	v_pk_mul_f32 v[158:159], v[56:57], v[148:149] op_sel_hi:[1,0]
	v_cvt_pk_bf16_f32 v160, v156, v157
	v_cvt_pk_bf16_f32 v161, v158, v159
	v_add_u32_e32 v134, 0x40100, v149
	global_store_dwordx2 v134, v[160:161], s[54:55]
	v_pk_mul_f32 v[156:157], v[50:51], v[148:149] op_sel_hi:[1,0]
	v_pk_mul_f32 v[158:159], v[52:53], v[148:149] op_sel_hi:[1,0]
	v_cvt_pk_bf16_f32 v160, v156, v157
	v_cvt_pk_bf16_f32 v161, v158, v159
	v_add_u32_e32 v134, 0x40120, v149
	global_store_dwordx2 v134, v[160:161], s[54:55]
	v_pk_mul_f32 v[156:157], v[46:47], v[150:151] op_sel_hi:[1,0]
	v_pk_mul_f32 v[158:159], v[48:49], v[150:151] op_sel_hi:[1,0]
	v_cvt_pk_bf16_f32 v160, v156, v157
	v_cvt_pk_bf16_f32 v161, v158, v159
	v_add_u32_e32 v134, 0x48000, v149
	global_store_dwordx2 v134, v[160:161], s[54:55]
	v_pk_mul_f32 v[156:157], v[42:43], v[150:151] op_sel_hi:[1,0]
	v_pk_mul_f32 v[158:159], v[44:45], v[150:151] op_sel_hi:[1,0]
	v_cvt_pk_bf16_f32 v160, v156, v157
	v_cvt_pk_bf16_f32 v161, v158, v159
	v_add_u32_e32 v134, 0x48020, v149
	global_store_dwordx2 v134, v[160:161], s[54:55]
	v_pk_mul_f32 v[156:157], v[38:39], v[150:151] op_sel_hi:[1,0]
	v_pk_mul_f32 v[158:159], v[40:41], v[150:151] op_sel_hi:[1,0]
	v_cvt_pk_bf16_f32 v160, v156, v157
	v_cvt_pk_bf16_f32 v161, v158, v159
	v_add_u32_e32 v134, 0x48100, v149
	global_store_dwordx2 v134, v[160:161], s[54:55]
	v_pk_mul_f32 v[156:157], v[34:35], v[150:151] op_sel_hi:[1,0]
	v_pk_mul_f32 v[158:159], v[36:37], v[150:151] op_sel_hi:[1,0]
	v_cvt_pk_bf16_f32 v160, v156, v157
	v_cvt_pk_bf16_f32 v161, v158, v159
	v_add_u32_e32 v134, 0x48120, v149
	global_store_dwordx2 v134, v[160:161], s[54:55]
	v_pk_mul_f32 v[156:157], v[30:31], v[152:153] op_sel_hi:[1,0]
	v_pk_mul_f32 v[158:159], v[32:33], v[152:153] op_sel_hi:[1,0]
	v_cvt_pk_bf16_f32 v160, v156, v157
	v_cvt_pk_bf16_f32 v161, v158, v159
	v_add_u32_e32 v134, 0x50000, v149
	global_store_dwordx2 v134, v[160:161], s[54:55]
	v_pk_mul_f32 v[156:157], v[26:27], v[152:153] op_sel_hi:[1,0]
	v_pk_mul_f32 v[158:159], v[28:29], v[152:153] op_sel_hi:[1,0]
	v_cvt_pk_bf16_f32 v160, v156, v157
	v_cvt_pk_bf16_f32 v161, v158, v159
	v_add_u32_e32 v134, 0x50020, v149
	global_store_dwordx2 v134, v[160:161], s[54:55]
	v_pk_mul_f32 v[156:157], v[22:23], v[152:153] op_sel_hi:[1,0]
	v_pk_mul_f32 v[158:159], v[24:25], v[152:153] op_sel_hi:[1,0]
	v_cvt_pk_bf16_f32 v160, v156, v157
	v_cvt_pk_bf16_f32 v161, v158, v159
	v_add_u32_e32 v134, 0x50100, v149
	global_store_dwordx2 v134, v[160:161], s[54:55]
	v_pk_mul_f32 v[156:157], v[18:19], v[152:153] op_sel_hi:[1,0]
	v_pk_mul_f32 v[158:159], v[20:21], v[152:153] op_sel_hi:[1,0]
	v_cvt_pk_bf16_f32 v160, v156, v157
	v_cvt_pk_bf16_f32 v161, v158, v159
	v_add_u32_e32 v134, 0x50120, v149
	global_store_dwordx2 v134, v[160:161], s[54:55]
	v_pk_mul_f32 v[156:157], v[14:15], v[154:155] op_sel_hi:[1,0]
	v_pk_mul_f32 v[158:159], v[16:17], v[154:155] op_sel_hi:[1,0]
	v_cvt_pk_bf16_f32 v160, v156, v157
	v_cvt_pk_bf16_f32 v161, v158, v159
	v_add_u32_e32 v134, 0x58000, v149
	global_store_dwordx2 v134, v[160:161], s[54:55]
	v_pk_mul_f32 v[156:157], v[10:11], v[154:155] op_sel_hi:[1,0]
	v_pk_mul_f32 v[158:159], v[12:13], v[154:155] op_sel_hi:[1,0]
	v_cvt_pk_bf16_f32 v160, v156, v157
	v_cvt_pk_bf16_f32 v161, v158, v159
	v_add_u32_e32 v134, 0x58020, v149
	global_store_dwordx2 v134, v[160:161], s[54:55]
	v_pk_mul_f32 v[156:157], v[6:7], v[154:155] op_sel_hi:[1,0]
	v_pk_mul_f32 v[158:159], v[8:9], v[154:155] op_sel_hi:[1,0]
	v_cvt_pk_bf16_f32 v160, v156, v157
	v_cvt_pk_bf16_f32 v161, v158, v159
	v_add_u32_e32 v134, 0x58100, v149
	global_store_dwordx2 v134, v[160:161], s[54:55]
	v_pk_mul_f32 v[156:157], v[2:3], v[154:155] op_sel_hi:[1,0]
	v_pk_mul_f32 v[158:159], v[4:5], v[154:155] op_sel_hi:[1,0]
	v_cvt_pk_bf16_f32 v160, v156, v157
	v_cvt_pk_bf16_f32 v161, v158, v159
	v_add_u32_e32 v134, 0x58120, v149
	global_store_dwordx2 v134, v[160:161], s[54:55]
	s_branch .LBB0_470
.Lmy_ri_v:
	s_sub_u32 s9, s0, 8
	s_cmp_lt_u32 s6, 64
	s_cbranch_scc0 .Lmy_ri_vs
	s_lshl_b32 s9, s9, 20
	s_lshr_b32 s17, s6, 3
	s_lshl_b32 s17, s17, 23
	s_add_u32 s9, s9, s17
	s_and_b32 s17, s6, 7
	s_lshl_b32 s17, s17, 9
	s_add_u32 s9, s9, s17
	v_lshlrev_b32_e32 v151, 12, v145
	v_lshl_add_u32 v151, v147, 1, v151
	v_add_u32_e32 v151, s9, v151
	s_waitcnt lgkmcnt(0)
	s_add_u32 s24, s26, 0x1000
	s_addc_u32 s25, s27, 0
	s_add_u32 s28, s26, 0x2000
	s_addc_u32 s29, s27, 0
	s_add_u32 s6, s26, 0x3000
	s_addc_u32 s7, s27, 0
	v_cvt_pk_bf16_f32 v160, v126, v127
	v_cvt_pk_bf16_f32 v161, v128, v129
	global_store_short v151, v160, s[26:27]
	global_store_short_d16_hi v151, v160, s[24:25]
	global_store_short v151, v161, s[28:29]
	global_store_short_d16_hi v151, v161, s[6:7]
	v_cvt_pk_bf16_f32 v160, v122, v123
	v_cvt_pk_bf16_f32 v161, v124, v125
	v_add_u32_e32 v172, 0x10000, v151
	global_store_short v172, v160, s[26:27]
	global_store_short_d16_hi v172, v160, s[24:25]
	global_store_short v172, v161, s[28:29]
	global_store_short_d16_hi v172, v161, s[6:7]
	v_cvt_pk_bf16_f32 v160, v118, v119
	v_cvt_pk_bf16_f32 v161, v120, v121
	v_add_u32_e32 v172, 0x80000, v151
	global_store_short v172, v160, s[26:27]
	global_store_short_d16_hi v172, v160, s[24:25]
	global_store_short v172, v161, s[28:29]
	global_store_short_d16_hi v172, v161, s[6:7]
	v_cvt_pk_bf16_f32 v160, v114, v115
	v_cvt_pk_bf16_f32 v161, v116, v117
	v_add_u32_e32 v172, 0x90000, v151
	global_store_short v172, v160, s[26:27]
	global_store_short_d16_hi v172, v160, s[24:25]
	global_store_short v172, v161, s[28:29]
	global_store_short_d16_hi v172, v161, s[6:7]
	v_cvt_pk_bf16_f32 v160, v110, v111
	v_cvt_pk_bf16_f32 v161, v112, v113
	v_add_u32_e32 v172, 0x20, v151
	global_store_short v172, v160, s[26:27]
	global_store_short_d16_hi v172, v160, s[24:25]
	global_store_short v172, v161, s[28:29]
	global_store_short_d16_hi v172, v161, s[6:7]
	v_cvt_pk_bf16_f32 v160, v106, v107
	v_cvt_pk_bf16_f32 v161, v108, v109
	v_add_u32_e32 v172, 0x10020, v151
	global_store_short v172, v160, s[26:27]
	global_store_short_d16_hi v172, v160, s[24:25]
	global_store_short v172, v161, s[28:29]
	global_store_short_d16_hi v172, v161, s[6:7]
	v_cvt_pk_bf16_f32 v160, v102, v103
	v_cvt_pk_bf16_f32 v161, v104, v105
	v_add_u32_e32 v172, 0x80020, v151
	global_store_short v172, v160, s[26:27]
	global_store_short_d16_hi v172, v160, s[24:25]
	global_store_short v172, v161, s[28:29]
	global_store_short_d16_hi v172, v161, s[6:7]
	v_cvt_pk_bf16_f32 v160, v98, v99
	v_cvt_pk_bf16_f32 v161, v100, v101
	v_add_u32_e32 v172, 0x90020, v151
	global_store_short v172, v160, s[26:27]
	global_store_short_d16_hi v172, v160, s[24:25]
	global_store_short v172, v161, s[28:29]
	global_store_short_d16_hi v172, v161, s[6:7]
	v_cvt_pk_bf16_f32 v160, v94, v95
	v_cvt_pk_bf16_f32 v161, v96, v97
	v_add_u32_e32 v172, 0x40, v151
	global_store_short v172, v160, s[26:27]
	global_store_short_d16_hi v172, v160, s[24:25]
	global_store_short v172, v161, s[28:29]
	global_store_short_d16_hi v172, v161, s[6:7]
	v_cvt_pk_bf16_f32 v160, v90, v91
	v_cvt_pk_bf16_f32 v161, v92, v93
	v_add_u32_e32 v172, 0x10040, v151
	global_store_short v172, v160, s[26:27]
	global_store_short_d16_hi v172, v160, s[24:25]
	global_store_short v172, v161, s[28:29]
	global_store_short_d16_hi v172, v161, s[6:7]
	v_cvt_pk_bf16_f32 v160, v86, v87
	v_cvt_pk_bf16_f32 v161, v88, v89
	v_add_u32_e32 v172, 0x80040, v151
	global_store_short v172, v160, s[26:27]
	global_store_short_d16_hi v172, v160, s[24:25]
	global_store_short v172, v161, s[28:29]
	global_store_short_d16_hi v172, v161, s[6:7]
	v_cvt_pk_bf16_f32 v160, v82, v83
	v_cvt_pk_bf16_f32 v161, v84, v85
	v_add_u32_e32 v172, 0x90040, v151
	global_store_short v172, v160, s[26:27]
	global_store_short_d16_hi v172, v160, s[24:25]
	global_store_short v172, v161, s[28:29]
	global_store_short_d16_hi v172, v161, s[6:7]
	v_cvt_pk_bf16_f32 v160, v78, v79
	v_cvt_pk_bf16_f32 v161, v80, v81
	v_add_u32_e32 v172, 0x60, v151
	global_store_short v172, v160, s[26:27]
	global_store_short_d16_hi v172, v160, s[24:25]
	global_store_short v172, v161, s[28:29]
	global_store_short_d16_hi v172, v161, s[6:7]
	v_cvt_pk_bf16_f32 v160, v74, v75
	v_cvt_pk_bf16_f32 v161, v76, v77
	v_add_u32_e32 v172, 0x10060, v151
	global_store_short v172, v160, s[26:27]
	global_store_short_d16_hi v172, v160, s[24:25]
	global_store_short v172, v161, s[28:29]
	global_store_short_d16_hi v172, v161, s[6:7]
	v_cvt_pk_bf16_f32 v160, v70, v71
	v_cvt_pk_bf16_f32 v161, v72, v73
	v_add_u32_e32 v172, 0x80060, v151
	global_store_short v172, v160, s[26:27]
	global_store_short_d16_hi v172, v160, s[24:25]
	global_store_short v172, v161, s[28:29]
	global_store_short_d16_hi v172, v161, s[6:7]
	v_cvt_pk_bf16_f32 v160, v66, v67
	v_cvt_pk_bf16_f32 v161, v68, v69
	v_add_u32_e32 v172, 0x90060, v151
	global_store_short v172, v160, s[26:27]
	global_store_short_d16_hi v172, v160, s[24:25]
	global_store_short v172, v161, s[28:29]
	global_store_short_d16_hi v172, v161, s[6:7]
	v_cvt_pk_bf16_f32 v160, v62, v63
	v_cvt_pk_bf16_f32 v161, v64, v65
	v_add_u32_e32 v172, 0x100, v151
	global_store_short v172, v160, s[26:27]
	global_store_short_d16_hi v172, v160, s[24:25]
	global_store_short v172, v161, s[28:29]
	global_store_short_d16_hi v172, v161, s[6:7]
	v_cvt_pk_bf16_f32 v160, v58, v59
	v_cvt_pk_bf16_f32 v161, v60, v61
	v_add_u32_e32 v172, 0x10100, v151
	global_store_short v172, v160, s[26:27]
	global_store_short_d16_hi v172, v160, s[24:25]
	global_store_short v172, v161, s[28:29]
	global_store_short_d16_hi v172, v161, s[6:7]
	v_cvt_pk_bf16_f32 v160, v54, v55
	v_cvt_pk_bf16_f32 v161, v56, v57
	v_add_u32_e32 v172, 0x80100, v151
	global_store_short v172, v160, s[26:27]
	global_store_short_d16_hi v172, v160, s[24:25]
	global_store_short v172, v161, s[28:29]
	global_store_short_d16_hi v172, v161, s[6:7]
	v_cvt_pk_bf16_f32 v160, v50, v51
	v_cvt_pk_bf16_f32 v161, v52, v53
	v_add_u32_e32 v172, 0x90100, v151
	global_store_short v172, v160, s[26:27]
	global_store_short_d16_hi v172, v160, s[24:25]
	global_store_short v172, v161, s[28:29]
	global_store_short_d16_hi v172, v161, s[6:7]
	v_cvt_pk_bf16_f32 v160, v46, v47
	v_cvt_pk_bf16_f32 v161, v48, v49
	v_add_u32_e32 v172, 0x120, v151
	global_store_short v172, v160, s[26:27]
	global_store_short_d16_hi v172, v160, s[24:25]
	global_store_short v172, v161, s[28:29]
	global_store_short_d16_hi v172, v161, s[6:7]
	v_cvt_pk_bf16_f32 v160, v42, v43
	v_cvt_pk_bf16_f32 v161, v44, v45
	v_add_u32_e32 v172, 0x10120, v151
	global_store_short v172, v160, s[26:27]
	global_store_short_d16_hi v172, v160, s[24:25]
	global_store_short v172, v161, s[28:29]
	global_store_short_d16_hi v172, v161, s[6:7]
	v_cvt_pk_bf16_f32 v160, v38, v39
	v_cvt_pk_bf16_f32 v161, v40, v41
	v_add_u32_e32 v172, 0x80120, v151
	global_store_short v172, v160, s[26:27]
	global_store_short_d16_hi v172, v160, s[24:25]
	global_store_short v172, v161, s[28:29]
	global_store_short_d16_hi v172, v161, s[6:7]
	v_cvt_pk_bf16_f32 v160, v34, v35
	v_cvt_pk_bf16_f32 v161, v36, v37
	v_add_u32_e32 v172, 0x90120, v151
	global_store_short v172, v160, s[26:27]
	global_store_short_d16_hi v172, v160, s[24:25]
	global_store_short v172, v161, s[28:29]
	global_store_short_d16_hi v172, v161, s[6:7]
	v_cvt_pk_bf16_f32 v160, v30, v31
	v_cvt_pk_bf16_f32 v161, v32, v33
	v_add_u32_e32 v172, 0x140, v151
	global_store_short v172, v160, s[26:27]
	global_store_short_d16_hi v172, v160, s[24:25]
	global_store_short v172, v161, s[28:29]
	global_store_short_d16_hi v172, v161, s[6:7]
	v_cvt_pk_bf16_f32 v160, v26, v27
	v_cvt_pk_bf16_f32 v161, v28, v29
	v_add_u32_e32 v172, 0x10140, v151
	global_store_short v172, v160, s[26:27]
	global_store_short_d16_hi v172, v160, s[24:25]
	global_store_short v172, v161, s[28:29]
	global_store_short_d16_hi v172, v161, s[6:7]
	v_cvt_pk_bf16_f32 v160, v22, v23
	v_cvt_pk_bf16_f32 v161, v24, v25
	v_add_u32_e32 v172, 0x80140, v151
	global_store_short v172, v160, s[26:27]
	global_store_short_d16_hi v172, v160, s[24:25]
	global_store_short v172, v161, s[28:29]
	global_store_short_d16_hi v172, v161, s[6:7]
	v_cvt_pk_bf16_f32 v160, v18, v19
	v_cvt_pk_bf16_f32 v161, v20, v21
	v_add_u32_e32 v172, 0x90140, v151
	global_store_short v172, v160, s[26:27]
	global_store_short_d16_hi v172, v160, s[24:25]
	global_store_short v172, v161, s[28:29]
	global_store_short_d16_hi v172, v161, s[6:7]
	v_cvt_pk_bf16_f32 v160, v14, v15
	v_cvt_pk_bf16_f32 v161, v16, v17
	v_add_u32_e32 v172, 0x160, v151
	global_store_short v172, v160, s[26:27]
	global_store_short_d16_hi v172, v160, s[24:25]
	global_store_short v172, v161, s[28:29]
	global_store_short_d16_hi v172, v161, s[6:7]
	v_cvt_pk_bf16_f32 v160, v10, v11
	v_cvt_pk_bf16_f32 v161, v12, v13
	v_add_u32_e32 v172, 0x10160, v151
	global_store_short v172, v160, s[26:27]
	global_store_short_d16_hi v172, v160, s[24:25]
	global_store_short v172, v161, s[28:29]
	global_store_short_d16_hi v172, v161, s[6:7]
	v_cvt_pk_bf16_f32 v160, v6, v7
	v_cvt_pk_bf16_f32 v161, v8, v9
	v_add_u32_e32 v172, 0x80160, v151
	global_store_short v172, v160, s[26:27]
	global_store_short_d16_hi v172, v160, s[24:25]
	global_store_short v172, v161, s[28:29]
	global_store_short_d16_hi v172, v161, s[6:7]
	v_cvt_pk_bf16_f32 v160, v2, v3
	v_cvt_pk_bf16_f32 v161, v4, v5
	v_add_u32_e32 v172, 0x90160, v151
	global_store_short v172, v160, s[26:27]
	global_store_short_d16_hi v172, v160, s[24:25]
	global_store_short v172, v161, s[28:29]
	global_store_short_d16_hi v172, v161, s[6:7]
	s_branch .LBB0_470
.Lmy_ri_vs:
	s_lshl_b32 s9, s9, 9
	v_lshlrev_b32_e32 v149, 12, v146
	v_lshl_add_u32 v149, v145, 1, v149
	v_add_u32_e32 v149, s9, v149
	s_waitcnt lgkmcnt(0)
	v_cvt_pk_bf16_f32 v160, v126, v127
	v_cvt_pk_bf16_f32 v161, v128, v129
	global_store_dwordx2 v149, v[160:161], s[56:57]
	v_cvt_pk_bf16_f32 v160, v122, v123
	v_cvt_pk_bf16_f32 v161, v124, v125
	v_add_u32_e32 v134, 0x20, v149
	global_store_dwordx2 v134, v[160:161], s[56:57]
	v_cvt_pk_bf16_f32 v160, v118, v119
	v_cvt_pk_bf16_f32 v161, v120, v121
	v_add_u32_e32 v134, 0x100, v149
	global_store_dwordx2 v134, v[160:161], s[56:57]
	v_cvt_pk_bf16_f32 v160, v114, v115
	v_cvt_pk_bf16_f32 v161, v116, v117
	v_add_u32_e32 v134, 0x120, v149
	global_store_dwordx2 v134, v[160:161], s[56:57]
	v_cvt_pk_bf16_f32 v160, v110, v111
	v_cvt_pk_bf16_f32 v161, v112, v113
	v_add_u32_e32 v134, 0x10000, v149
	global_store_dwordx2 v134, v[160:161], s[56:57]
	v_cvt_pk_bf16_f32 v160, v106, v107
	v_cvt_pk_bf16_f32 v161, v108, v109
	v_add_u32_e32 v134, 0x10020, v149
	global_store_dwordx2 v134, v[160:161], s[56:57]
	v_cvt_pk_bf16_f32 v160, v102, v103
	v_cvt_pk_bf16_f32 v161, v104, v105
	v_add_u32_e32 v134, 0x10100, v149
	global_store_dwordx2 v134, v[160:161], s[56:57]
	v_cvt_pk_bf16_f32 v160, v98, v99
	v_cvt_pk_bf16_f32 v161, v100, v101
	v_add_u32_e32 v134, 0x10120, v149
	global_store_dwordx2 v134, v[160:161], s[56:57]
	v_cvt_pk_bf16_f32 v160, v94, v95
	v_cvt_pk_bf16_f32 v161, v96, v97
	v_add_u32_e32 v134, 0x20000, v149
	global_store_dwordx2 v134, v[160:161], s[56:57]
	v_cvt_pk_bf16_f32 v160, v90, v91
	v_cvt_pk_bf16_f32 v161, v92, v93
	v_add_u32_e32 v134, 0x20020, v149
	global_store_dwordx2 v134, v[160:161], s[56:57]
	v_cvt_pk_bf16_f32 v160, v86, v87
	v_cvt_pk_bf16_f32 v161, v88, v89
	v_add_u32_e32 v134, 0x20100, v149
	global_store_dwordx2 v134, v[160:161], s[56:57]
	v_cvt_pk_bf16_f32 v160, v82, v83
	v_cvt_pk_bf16_f32 v161, v84, v85
	v_add_u32_e32 v134, 0x20120, v149
	global_store_dwordx2 v134, v[160:161], s[56:57]
	v_cvt_pk_bf16_f32 v160, v78, v79
	v_cvt_pk_bf16_f32 v161, v80, v81
	v_add_u32_e32 v134, 0x30000, v149
	global_store_dwordx2 v134, v[160:161], s[56:57]
	v_cvt_pk_bf16_f32 v160, v74, v75
	v_cvt_pk_bf16_f32 v161, v76, v77
	v_add_u32_e32 v134, 0x30020, v149
	global_store_dwordx2 v134, v[160:161], s[56:57]
	v_cvt_pk_bf16_f32 v160, v70, v71
	v_cvt_pk_bf16_f32 v161, v72, v73
	v_add_u32_e32 v134, 0x30100, v149
	global_store_dwordx2 v134, v[160:161], s[56:57]
	v_cvt_pk_bf16_f32 v160, v66, v67
	v_cvt_pk_bf16_f32 v161, v68, v69
	v_add_u32_e32 v134, 0x30120, v149
	global_store_dwordx2 v134, v[160:161], s[56:57]
	v_cvt_pk_bf16_f32 v160, v62, v63
	v_cvt_pk_bf16_f32 v161, v64, v65
	v_add_u32_e32 v134, 0x80000, v149
	global_store_dwordx2 v134, v[160:161], s[56:57]
	v_cvt_pk_bf16_f32 v160, v58, v59
	v_cvt_pk_bf16_f32 v161, v60, v61
	v_add_u32_e32 v134, 0x80020, v149
	global_store_dwordx2 v134, v[160:161], s[56:57]
	v_cvt_pk_bf16_f32 v160, v54, v55
	v_cvt_pk_bf16_f32 v161, v56, v57
	v_add_u32_e32 v134, 0x80100, v149
	global_store_dwordx2 v134, v[160:161], s[56:57]
	v_cvt_pk_bf16_f32 v160, v50, v51
	v_cvt_pk_bf16_f32 v161, v52, v53
	v_add_u32_e32 v134, 0x80120, v149
	global_store_dwordx2 v134, v[160:161], s[56:57]
	v_cvt_pk_bf16_f32 v160, v46, v47
	v_cvt_pk_bf16_f32 v161, v48, v49
	v_add_u32_e32 v134, 0x90000, v149
	global_store_dwordx2 v134, v[160:161], s[56:57]
	v_cvt_pk_bf16_f32 v160, v42, v43
	v_cvt_pk_bf16_f32 v161, v44, v45
	v_add_u32_e32 v134, 0x90020, v149
	global_store_dwordx2 v134, v[160:161], s[56:57]
	v_cvt_pk_bf16_f32 v160, v38, v39
	v_cvt_pk_bf16_f32 v161, v40, v41
	v_add_u32_e32 v134, 0x90100, v149
	global_store_dwordx2 v134, v[160:161], s[56:57]
	v_cvt_pk_bf16_f32 v160, v34, v35
	v_cvt_pk_bf16_f32 v161, v36, v37
	v_add_u32_e32 v134, 0x90120, v149
	global_store_dwordx2 v134, v[160:161], s[56:57]
	v_cvt_pk_bf16_f32 v160, v30, v31
	v_cvt_pk_bf16_f32 v161, v32, v33
	v_add_u32_e32 v134, 0xa0000, v149
	global_store_dwordx2 v134, v[160:161], s[56:57]
	v_cvt_pk_bf16_f32 v160, v26, v27
	v_cvt_pk_bf16_f32 v161, v28, v29
	v_add_u32_e32 v134, 0xa0020, v149
	global_store_dwordx2 v134, v[160:161], s[56:57]
	v_cvt_pk_bf16_f32 v160, v22, v23
	v_cvt_pk_bf16_f32 v161, v24, v25
	v_add_u32_e32 v134, 0xa0100, v149
	global_store_dwordx2 v134, v[160:161], s[56:57]
	v_cvt_pk_bf16_f32 v160, v18, v19
	v_cvt_pk_bf16_f32 v161, v20, v21
	v_add_u32_e32 v134, 0xa0120, v149
	global_store_dwordx2 v134, v[160:161], s[56:57]
	v_cvt_pk_bf16_f32 v160, v14, v15
	v_cvt_pk_bf16_f32 v161, v16, v17
	v_add_u32_e32 v134, 0xb0000, v149
	global_store_dwordx2 v134, v[160:161], s[56:57]
	v_cvt_pk_bf16_f32 v160, v10, v11
	v_cvt_pk_bf16_f32 v161, v12, v13
	v_add_u32_e32 v134, 0xb0020, v149
	global_store_dwordx2 v134, v[160:161], s[56:57]
	v_cvt_pk_bf16_f32 v160, v6, v7
	v_cvt_pk_bf16_f32 v161, v8, v9
	v_add_u32_e32 v134, 0xb0100, v149
	global_store_dwordx2 v134, v[160:161], s[56:57]
	v_cvt_pk_bf16_f32 v160, v2, v3
	v_cvt_pk_bf16_f32 v161, v4, v5
	v_add_u32_e32 v134, 0xb0120, v149
	global_store_dwordx2 v134, v[160:161], s[56:57]
	s_branch .LBB0_470
.Lmy_ri_g:
	s_sub_u32 s9, s0, 16
	s_lshl_b32 s9, s9, 9
	v_lshlrev_b32_e32 v149, 12, v146
	v_lshl_add_u32 v149, v145, 1, v149
	v_add_u32_e32 v149, s9, v149
	s_waitcnt lgkmcnt(0)
	v_mul_f32_e32 v156, 0xbfb8aa3b, v126
	v_mul_f32_e32 v157, 0xbfb8aa3b, v127
	v_mul_f32_e32 v158, 0xbfb8aa3b, v128
	v_mul_f32_e32 v159, 0xbfb8aa3b, v129
	v_exp_f32_e32 v156, v156
	v_exp_f32_e32 v157, v157
	v_exp_f32_e32 v158, v158
	v_exp_f32_e32 v159, v159
	v_add_f32_e32 v156, 1.0, v156
	v_add_f32_e32 v157, 1.0, v157
	v_add_f32_e32 v158, 1.0, v158
	v_add_f32_e32 v159, 1.0, v159
	v_rcp_f32_e32 v156, v156
	v_rcp_f32_e32 v157, v157
	v_rcp_f32_e32 v158, v158
	v_rcp_f32_e32 v159, v159
	v_mul_f32_e32 v156, v126, v156
	v_mul_f32_e32 v157, v127, v157
	v_mul_f32_e32 v158, v128, v158
	v_mul_f32_e32 v159, v129, v159
	v_cvt_pk_bf16_f32 v160, v156, v157
	v_cvt_pk_bf16_f32 v161, v158, v159
	global_store_dwordx2 v149, v[160:161], s[58:59]
	v_mul_f32_e32 v156, 0xbfb8aa3b, v122
	v_mul_f32_e32 v157, 0xbfb8aa3b, v123
	v_mul_f32_e32 v158, 0xbfb8aa3b, v124
	v_mul_f32_e32 v159, 0xbfb8aa3b, v125
	v_exp_f32_e32 v156, v156
	v_exp_f32_e32 v157, v157
	v_exp_f32_e32 v158, v158
	v_exp_f32_e32 v159, v159
	v_add_f32_e32 v156, 1.0, v156
	v_add_f32_e32 v157, 1.0, v157
	v_add_f32_e32 v158, 1.0, v158
	v_add_f32_e32 v159, 1.0, v159
	v_rcp_f32_e32 v156, v156
	v_rcp_f32_e32 v157, v157
	v_rcp_f32_e32 v158, v158
	v_rcp_f32_e32 v159, v159
	v_mul_f32_e32 v156, v122, v156
	v_mul_f32_e32 v157, v123, v157
	v_mul_f32_e32 v158, v124, v158
	v_mul_f32_e32 v159, v125, v159
	v_cvt_pk_bf16_f32 v160, v156, v157
	v_cvt_pk_bf16_f32 v161, v158, v159
	v_add_u32_e32 v134, 0x20, v149
	global_store_dwordx2 v134, v[160:161], s[58:59]
	v_mul_f32_e32 v156, 0xbfb8aa3b, v118
	v_mul_f32_e32 v157, 0xbfb8aa3b, v119
	v_mul_f32_e32 v158, 0xbfb8aa3b, v120
	v_mul_f32_e32 v159, 0xbfb8aa3b, v121
	v_exp_f32_e32 v156, v156
	v_exp_f32_e32 v157, v157
	v_exp_f32_e32 v158, v158
	v_exp_f32_e32 v159, v159
	v_add_f32_e32 v156, 1.0, v156
	v_add_f32_e32 v157, 1.0, v157
	v_add_f32_e32 v158, 1.0, v158
	v_add_f32_e32 v159, 1.0, v159
	v_rcp_f32_e32 v156, v156
	v_rcp_f32_e32 v157, v157
	v_rcp_f32_e32 v158, v158
	v_rcp_f32_e32 v159, v159
	v_mul_f32_e32 v156, v118, v156
	v_mul_f32_e32 v157, v119, v157
	v_mul_f32_e32 v158, v120, v158
	v_mul_f32_e32 v159, v121, v159
	v_cvt_pk_bf16_f32 v160, v156, v157
	v_cvt_pk_bf16_f32 v161, v158, v159
	v_add_u32_e32 v134, 0x100, v149
	global_store_dwordx2 v134, v[160:161], s[58:59]
	v_mul_f32_e32 v156, 0xbfb8aa3b, v114
	v_mul_f32_e32 v157, 0xbfb8aa3b, v115
	v_mul_f32_e32 v158, 0xbfb8aa3b, v116
	v_mul_f32_e32 v159, 0xbfb8aa3b, v117
	v_exp_f32_e32 v156, v156
	v_exp_f32_e32 v157, v157
	v_exp_f32_e32 v158, v158
	v_exp_f32_e32 v159, v159
	v_add_f32_e32 v156, 1.0, v156
	v_add_f32_e32 v157, 1.0, v157
	v_add_f32_e32 v158, 1.0, v158
	v_add_f32_e32 v159, 1.0, v159
	v_rcp_f32_e32 v156, v156
	v_rcp_f32_e32 v157, v157
	v_rcp_f32_e32 v158, v158
	v_rcp_f32_e32 v159, v159
	v_mul_f32_e32 v156, v114, v156
	v_mul_f32_e32 v157, v115, v157
	v_mul_f32_e32 v158, v116, v158
	v_mul_f32_e32 v159, v117, v159
	v_cvt_pk_bf16_f32 v160, v156, v157
	v_cvt_pk_bf16_f32 v161, v158, v159
	v_add_u32_e32 v134, 0x120, v149
	global_store_dwordx2 v134, v[160:161], s[58:59]
	v_mul_f32_e32 v156, 0xbfb8aa3b, v110
	v_mul_f32_e32 v157, 0xbfb8aa3b, v111
	v_mul_f32_e32 v158, 0xbfb8aa3b, v112
	v_mul_f32_e32 v159, 0xbfb8aa3b, v113
	v_exp_f32_e32 v156, v156
	v_exp_f32_e32 v157, v157
	v_exp_f32_e32 v158, v158
	v_exp_f32_e32 v159, v159
	v_add_f32_e32 v156, 1.0, v156
	v_add_f32_e32 v157, 1.0, v157
	v_add_f32_e32 v158, 1.0, v158
	v_add_f32_e32 v159, 1.0, v159
	v_rcp_f32_e32 v156, v156
	v_rcp_f32_e32 v157, v157
	v_rcp_f32_e32 v158, v158
	v_rcp_f32_e32 v159, v159
	v_mul_f32_e32 v156, v110, v156
	v_mul_f32_e32 v157, v111, v157
	v_mul_f32_e32 v158, v112, v158
	v_mul_f32_e32 v159, v113, v159
	v_cvt_pk_bf16_f32 v160, v156, v157
	v_cvt_pk_bf16_f32 v161, v158, v159
	v_add_u32_e32 v134, 0x10000, v149
	global_store_dwordx2 v134, v[160:161], s[58:59]
	v_mul_f32_e32 v156, 0xbfb8aa3b, v106
	v_mul_f32_e32 v157, 0xbfb8aa3b, v107
	v_mul_f32_e32 v158, 0xbfb8aa3b, v108
	v_mul_f32_e32 v159, 0xbfb8aa3b, v109
	v_exp_f32_e32 v156, v156
	v_exp_f32_e32 v157, v157
	v_exp_f32_e32 v158, v158
	v_exp_f32_e32 v159, v159
	v_add_f32_e32 v156, 1.0, v156
	v_add_f32_e32 v157, 1.0, v157
	v_add_f32_e32 v158, 1.0, v158
	v_add_f32_e32 v159, 1.0, v159
	v_rcp_f32_e32 v156, v156
	v_rcp_f32_e32 v157, v157
	v_rcp_f32_e32 v158, v158
	v_rcp_f32_e32 v159, v159
	v_mul_f32_e32 v156, v106, v156
	v_mul_f32_e32 v157, v107, v157
	v_mul_f32_e32 v158, v108, v158
	v_mul_f32_e32 v159, v109, v159
	v_cvt_pk_bf16_f32 v160, v156, v157
	v_cvt_pk_bf16_f32 v161, v158, v159
	v_add_u32_e32 v134, 0x10020, v149
	global_store_dwordx2 v134, v[160:161], s[58:59]
	v_mul_f32_e32 v156, 0xbfb8aa3b, v102
	v_mul_f32_e32 v157, 0xbfb8aa3b, v103
	v_mul_f32_e32 v158, 0xbfb8aa3b, v104
	v_mul_f32_e32 v159, 0xbfb8aa3b, v105
	v_exp_f32_e32 v156, v156
	v_exp_f32_e32 v157, v157
	v_exp_f32_e32 v158, v158
	v_exp_f32_e32 v159, v159
	v_add_f32_e32 v156, 1.0, v156
	v_add_f32_e32 v157, 1.0, v157
	v_add_f32_e32 v158, 1.0, v158
	v_add_f32_e32 v159, 1.0, v159
	v_rcp_f32_e32 v156, v156
	v_rcp_f32_e32 v157, v157
	v_rcp_f32_e32 v158, v158
	v_rcp_f32_e32 v159, v159
	v_mul_f32_e32 v156, v102, v156
	v_mul_f32_e32 v157, v103, v157
	v_mul_f32_e32 v158, v104, v158
	v_mul_f32_e32 v159, v105, v159
	v_cvt_pk_bf16_f32 v160, v156, v157
	v_cvt_pk_bf16_f32 v161, v158, v159
	v_add_u32_e32 v134, 0x10100, v149
	global_store_dwordx2 v134, v[160:161], s[58:59]
	v_mul_f32_e32 v156, 0xbfb8aa3b, v98
	v_mul_f32_e32 v157, 0xbfb8aa3b, v99
	v_mul_f32_e32 v158, 0xbfb8aa3b, v100
	v_mul_f32_e32 v159, 0xbfb8aa3b, v101
	v_exp_f32_e32 v156, v156
	v_exp_f32_e32 v157, v157
	v_exp_f32_e32 v158, v158
	v_exp_f32_e32 v159, v159
	v_add_f32_e32 v156, 1.0, v156
	v_add_f32_e32 v157, 1.0, v157
	v_add_f32_e32 v158, 1.0, v158
	v_add_f32_e32 v159, 1.0, v159
	v_rcp_f32_e32 v156, v156
	v_rcp_f32_e32 v157, v157
	v_rcp_f32_e32 v158, v158
	v_rcp_f32_e32 v159, v159
	v_mul_f32_e32 v156, v98, v156
	v_mul_f32_e32 v157, v99, v157
	v_mul_f32_e32 v158, v100, v158
	v_mul_f32_e32 v159, v101, v159
	v_cvt_pk_bf16_f32 v160, v156, v157
	v_cvt_pk_bf16_f32 v161, v158, v159
	v_add_u32_e32 v134, 0x10120, v149
	global_store_dwordx2 v134, v[160:161], s[58:59]
	v_mul_f32_e32 v156, 0xbfb8aa3b, v94
	v_mul_f32_e32 v157, 0xbfb8aa3b, v95
	v_mul_f32_e32 v158, 0xbfb8aa3b, v96
	v_mul_f32_e32 v159, 0xbfb8aa3b, v97
	v_exp_f32_e32 v156, v156
	v_exp_f32_e32 v157, v157
	v_exp_f32_e32 v158, v158
	v_exp_f32_e32 v159, v159
	v_add_f32_e32 v156, 1.0, v156
	v_add_f32_e32 v157, 1.0, v157
	v_add_f32_e32 v158, 1.0, v158
	v_add_f32_e32 v159, 1.0, v159
	v_rcp_f32_e32 v156, v156
	v_rcp_f32_e32 v157, v157
	v_rcp_f32_e32 v158, v158
	v_rcp_f32_e32 v159, v159
	v_mul_f32_e32 v156, v94, v156
	v_mul_f32_e32 v157, v95, v157
	v_mul_f32_e32 v158, v96, v158
	v_mul_f32_e32 v159, v97, v159
	v_cvt_pk_bf16_f32 v160, v156, v157
	v_cvt_pk_bf16_f32 v161, v158, v159
	v_add_u32_e32 v134, 0x20000, v149
	global_store_dwordx2 v134, v[160:161], s[58:59]
	v_mul_f32_e32 v156, 0xbfb8aa3b, v90
	v_mul_f32_e32 v157, 0xbfb8aa3b, v91
	v_mul_f32_e32 v158, 0xbfb8aa3b, v92
	v_mul_f32_e32 v159, 0xbfb8aa3b, v93
	v_exp_f32_e32 v156, v156
	v_exp_f32_e32 v157, v157
	v_exp_f32_e32 v158, v158
	v_exp_f32_e32 v159, v159
	v_add_f32_e32 v156, 1.0, v156
	v_add_f32_e32 v157, 1.0, v157
	v_add_f32_e32 v158, 1.0, v158
	v_add_f32_e32 v159, 1.0, v159
	v_rcp_f32_e32 v156, v156
	v_rcp_f32_e32 v157, v157
	v_rcp_f32_e32 v158, v158
	v_rcp_f32_e32 v159, v159
	v_mul_f32_e32 v156, v90, v156
	v_mul_f32_e32 v157, v91, v157
	v_mul_f32_e32 v158, v92, v158
	v_mul_f32_e32 v159, v93, v159
	v_cvt_pk_bf16_f32 v160, v156, v157
	v_cvt_pk_bf16_f32 v161, v158, v159
	v_add_u32_e32 v134, 0x20020, v149
	global_store_dwordx2 v134, v[160:161], s[58:59]
	v_mul_f32_e32 v156, 0xbfb8aa3b, v86
	v_mul_f32_e32 v157, 0xbfb8aa3b, v87
	v_mul_f32_e32 v158, 0xbfb8aa3b, v88
	v_mul_f32_e32 v159, 0xbfb8aa3b, v89
	v_exp_f32_e32 v156, v156
	v_exp_f32_e32 v157, v157
	v_exp_f32_e32 v158, v158
	v_exp_f32_e32 v159, v159
	v_add_f32_e32 v156, 1.0, v156
	v_add_f32_e32 v157, 1.0, v157
	v_add_f32_e32 v158, 1.0, v158
	v_add_f32_e32 v159, 1.0, v159
	v_rcp_f32_e32 v156, v156
	v_rcp_f32_e32 v157, v157
	v_rcp_f32_e32 v158, v158
	v_rcp_f32_e32 v159, v159
	v_mul_f32_e32 v156, v86, v156
	v_mul_f32_e32 v157, v87, v157
	v_mul_f32_e32 v158, v88, v158
	v_mul_f32_e32 v159, v89, v159
	v_cvt_pk_bf16_f32 v160, v156, v157
	v_cvt_pk_bf16_f32 v161, v158, v159
	v_add_u32_e32 v134, 0x20100, v149
	global_store_dwordx2 v134, v[160:161], s[58:59]
	v_mul_f32_e32 v156, 0xbfb8aa3b, v82
	v_mul_f32_e32 v157, 0xbfb8aa3b, v83
	v_mul_f32_e32 v158, 0xbfb8aa3b, v84
	v_mul_f32_e32 v159, 0xbfb8aa3b, v85
	v_exp_f32_e32 v156, v156
	v_exp_f32_e32 v157, v157
	v_exp_f32_e32 v158, v158
	v_exp_f32_e32 v159, v159
	v_add_f32_e32 v156, 1.0, v156
	v_add_f32_e32 v157, 1.0, v157
	v_add_f32_e32 v158, 1.0, v158
	v_add_f32_e32 v159, 1.0, v159
	v_rcp_f32_e32 v156, v156
	v_rcp_f32_e32 v157, v157
	v_rcp_f32_e32 v158, v158
	v_rcp_f32_e32 v159, v159
	v_mul_f32_e32 v156, v82, v156
	v_mul_f32_e32 v157, v83, v157
	v_mul_f32_e32 v158, v84, v158
	v_mul_f32_e32 v159, v85, v159
	v_cvt_pk_bf16_f32 v160, v156, v157
	v_cvt_pk_bf16_f32 v161, v158, v159
	v_add_u32_e32 v134, 0x20120, v149
	global_store_dwordx2 v134, v[160:161], s[58:59]
	v_mul_f32_e32 v156, 0xbfb8aa3b, v78
	v_mul_f32_e32 v157, 0xbfb8aa3b, v79
	v_mul_f32_e32 v158, 0xbfb8aa3b, v80
	v_mul_f32_e32 v159, 0xbfb8aa3b, v81
	v_exp_f32_e32 v156, v156
	v_exp_f32_e32 v157, v157
	v_exp_f32_e32 v158, v158
	v_exp_f32_e32 v159, v159
	v_add_f32_e32 v156, 1.0, v156
	v_add_f32_e32 v157, 1.0, v157
	v_add_f32_e32 v158, 1.0, v158
	v_add_f32_e32 v159, 1.0, v159
	v_rcp_f32_e32 v156, v156
	v_rcp_f32_e32 v157, v157
	v_rcp_f32_e32 v158, v158
	v_rcp_f32_e32 v159, v159
	v_mul_f32_e32 v156, v78, v156
	v_mul_f32_e32 v157, v79, v157
	v_mul_f32_e32 v158, v80, v158
	v_mul_f32_e32 v159, v81, v159
	v_cvt_pk_bf16_f32 v160, v156, v157
	v_cvt_pk_bf16_f32 v161, v158, v159
	v_add_u32_e32 v134, 0x30000, v149
	global_store_dwordx2 v134, v[160:161], s[58:59]
	v_mul_f32_e32 v156, 0xbfb8aa3b, v74
	v_mul_f32_e32 v157, 0xbfb8aa3b, v75
	v_mul_f32_e32 v158, 0xbfb8aa3b, v76
	v_mul_f32_e32 v159, 0xbfb8aa3b, v77
	v_exp_f32_e32 v156, v156
	v_exp_f32_e32 v157, v157
	v_exp_f32_e32 v158, v158
	v_exp_f32_e32 v159, v159
	v_add_f32_e32 v156, 1.0, v156
	v_add_f32_e32 v157, 1.0, v157
	v_add_f32_e32 v158, 1.0, v158
	v_add_f32_e32 v159, 1.0, v159
	v_rcp_f32_e32 v156, v156
	v_rcp_f32_e32 v157, v157
	v_rcp_f32_e32 v158, v158
	v_rcp_f32_e32 v159, v159
	v_mul_f32_e32 v156, v74, v156
	v_mul_f32_e32 v157, v75, v157
	v_mul_f32_e32 v158, v76, v158
	v_mul_f32_e32 v159, v77, v159
	v_cvt_pk_bf16_f32 v160, v156, v157
	v_cvt_pk_bf16_f32 v161, v158, v159
	v_add_u32_e32 v134, 0x30020, v149
	global_store_dwordx2 v134, v[160:161], s[58:59]
	v_mul_f32_e32 v156, 0xbfb8aa3b, v70
	v_mul_f32_e32 v157, 0xbfb8aa3b, v71
	v_mul_f32_e32 v158, 0xbfb8aa3b, v72
	v_mul_f32_e32 v159, 0xbfb8aa3b, v73
	v_exp_f32_e32 v156, v156
	v_exp_f32_e32 v157, v157
	v_exp_f32_e32 v158, v158
	v_exp_f32_e32 v159, v159
	v_add_f32_e32 v156, 1.0, v156
	v_add_f32_e32 v157, 1.0, v157
	v_add_f32_e32 v158, 1.0, v158
	v_add_f32_e32 v159, 1.0, v159
	v_rcp_f32_e32 v156, v156
	v_rcp_f32_e32 v157, v157
	v_rcp_f32_e32 v158, v158
	v_rcp_f32_e32 v159, v159
	v_mul_f32_e32 v156, v70, v156
	v_mul_f32_e32 v157, v71, v157
	v_mul_f32_e32 v158, v72, v158
	v_mul_f32_e32 v159, v73, v159
	v_cvt_pk_bf16_f32 v160, v156, v157
	v_cvt_pk_bf16_f32 v161, v158, v159
	v_add_u32_e32 v134, 0x30100, v149
	global_store_dwordx2 v134, v[160:161], s[58:59]
	v_mul_f32_e32 v156, 0xbfb8aa3b, v66
	v_mul_f32_e32 v157, 0xbfb8aa3b, v67
	v_mul_f32_e32 v158, 0xbfb8aa3b, v68
	v_mul_f32_e32 v159, 0xbfb8aa3b, v69
	v_exp_f32_e32 v156, v156
	v_exp_f32_e32 v157, v157
	v_exp_f32_e32 v158, v158
	v_exp_f32_e32 v159, v159
	v_add_f32_e32 v156, 1.0, v156
	v_add_f32_e32 v157, 1.0, v157
	v_add_f32_e32 v158, 1.0, v158
	v_add_f32_e32 v159, 1.0, v159
	v_rcp_f32_e32 v156, v156
	v_rcp_f32_e32 v157, v157
	v_rcp_f32_e32 v158, v158
	v_rcp_f32_e32 v159, v159
	v_mul_f32_e32 v156, v66, v156
	v_mul_f32_e32 v157, v67, v157
	v_mul_f32_e32 v158, v68, v158
	v_mul_f32_e32 v159, v69, v159
	v_cvt_pk_bf16_f32 v160, v156, v157
	v_cvt_pk_bf16_f32 v161, v158, v159
	v_add_u32_e32 v134, 0x30120, v149
	global_store_dwordx2 v134, v[160:161], s[58:59]
	v_mul_f32_e32 v156, 0xbfb8aa3b, v62
	v_mul_f32_e32 v157, 0xbfb8aa3b, v63
	v_mul_f32_e32 v158, 0xbfb8aa3b, v64
	v_mul_f32_e32 v159, 0xbfb8aa3b, v65
	v_exp_f32_e32 v156, v156
	v_exp_f32_e32 v157, v157
	v_exp_f32_e32 v158, v158
	v_exp_f32_e32 v159, v159
	v_add_f32_e32 v156, 1.0, v156
	v_add_f32_e32 v157, 1.0, v157
	v_add_f32_e32 v158, 1.0, v158
	v_add_f32_e32 v159, 1.0, v159
	v_rcp_f32_e32 v156, v156
	v_rcp_f32_e32 v157, v157
	v_rcp_f32_e32 v158, v158
	v_rcp_f32_e32 v159, v159
	v_mul_f32_e32 v156, v62, v156
	v_mul_f32_e32 v157, v63, v157
	v_mul_f32_e32 v158, v64, v158
	v_mul_f32_e32 v159, v65, v159
	v_cvt_pk_bf16_f32 v160, v156, v157
	v_cvt_pk_bf16_f32 v161, v158, v159
	v_add_u32_e32 v134, 0x80000, v149
	global_store_dwordx2 v134, v[160:161], s[58:59]
	v_mul_f32_e32 v156, 0xbfb8aa3b, v58
	v_mul_f32_e32 v157, 0xbfb8aa3b, v59
	v_mul_f32_e32 v158, 0xbfb8aa3b, v60
	v_mul_f32_e32 v159, 0xbfb8aa3b, v61
	v_exp_f32_e32 v156, v156
	v_exp_f32_e32 v157, v157
	v_exp_f32_e32 v158, v158
	v_exp_f32_e32 v159, v159
	v_add_f32_e32 v156, 1.0, v156
	v_add_f32_e32 v157, 1.0, v157
	v_add_f32_e32 v158, 1.0, v158
	v_add_f32_e32 v159, 1.0, v159
	v_rcp_f32_e32 v156, v156
	v_rcp_f32_e32 v157, v157
	v_rcp_f32_e32 v158, v158
	v_rcp_f32_e32 v159, v159
	v_mul_f32_e32 v156, v58, v156
	v_mul_f32_e32 v157, v59, v157
	v_mul_f32_e32 v158, v60, v158
	v_mul_f32_e32 v159, v61, v159
	v_cvt_pk_bf16_f32 v160, v156, v157
	v_cvt_pk_bf16_f32 v161, v158, v159
	v_add_u32_e32 v134, 0x80020, v149
	global_store_dwordx2 v134, v[160:161], s[58:59]
	v_mul_f32_e32 v156, 0xbfb8aa3b, v54
	v_mul_f32_e32 v157, 0xbfb8aa3b, v55
	v_mul_f32_e32 v158, 0xbfb8aa3b, v56
	v_mul_f32_e32 v159, 0xbfb8aa3b, v57
	v_exp_f32_e32 v156, v156
	v_exp_f32_e32 v157, v157
	v_exp_f32_e32 v158, v158
	v_exp_f32_e32 v159, v159
	v_add_f32_e32 v156, 1.0, v156
	v_add_f32_e32 v157, 1.0, v157
	v_add_f32_e32 v158, 1.0, v158
	v_add_f32_e32 v159, 1.0, v159
	v_rcp_f32_e32 v156, v156
	v_rcp_f32_e32 v157, v157
	v_rcp_f32_e32 v158, v158
	v_rcp_f32_e32 v159, v159
	v_mul_f32_e32 v156, v54, v156
	v_mul_f32_e32 v157, v55, v157
	v_mul_f32_e32 v158, v56, v158
	v_mul_f32_e32 v159, v57, v159
	v_cvt_pk_bf16_f32 v160, v156, v157
	v_cvt_pk_bf16_f32 v161, v158, v159
	v_add_u32_e32 v134, 0x80100, v149
	global_store_dwordx2 v134, v[160:161], s[58:59]
	v_mul_f32_e32 v156, 0xbfb8aa3b, v50
	v_mul_f32_e32 v157, 0xbfb8aa3b, v51
	v_mul_f32_e32 v158, 0xbfb8aa3b, v52
	v_mul_f32_e32 v159, 0xbfb8aa3b, v53
	v_exp_f32_e32 v156, v156
	v_exp_f32_e32 v157, v157
	v_exp_f32_e32 v158, v158
	v_exp_f32_e32 v159, v159
	v_add_f32_e32 v156, 1.0, v156
	v_add_f32_e32 v157, 1.0, v157
	v_add_f32_e32 v158, 1.0, v158
	v_add_f32_e32 v159, 1.0, v159
	v_rcp_f32_e32 v156, v156
	v_rcp_f32_e32 v157, v157
	v_rcp_f32_e32 v158, v158
	v_rcp_f32_e32 v159, v159
	v_mul_f32_e32 v156, v50, v156
	v_mul_f32_e32 v157, v51, v157
	v_mul_f32_e32 v158, v52, v158
	v_mul_f32_e32 v159, v53, v159
	v_cvt_pk_bf16_f32 v160, v156, v157
	v_cvt_pk_bf16_f32 v161, v158, v159
	v_add_u32_e32 v134, 0x80120, v149
	global_store_dwordx2 v134, v[160:161], s[58:59]
	v_mul_f32_e32 v156, 0xbfb8aa3b, v46
	v_mul_f32_e32 v157, 0xbfb8aa3b, v47
	v_mul_f32_e32 v158, 0xbfb8aa3b, v48
	v_mul_f32_e32 v159, 0xbfb8aa3b, v49
	v_exp_f32_e32 v156, v156
	v_exp_f32_e32 v157, v157
	v_exp_f32_e32 v158, v158
	v_exp_f32_e32 v159, v159
	v_add_f32_e32 v156, 1.0, v156
	v_add_f32_e32 v157, 1.0, v157
	v_add_f32_e32 v158, 1.0, v158
	v_add_f32_e32 v159, 1.0, v159
	v_rcp_f32_e32 v156, v156
	v_rcp_f32_e32 v157, v157
	v_rcp_f32_e32 v158, v158
	v_rcp_f32_e32 v159, v159
	v_mul_f32_e32 v156, v46, v156
	v_mul_f32_e32 v157, v47, v157
	v_mul_f32_e32 v158, v48, v158
	v_mul_f32_e32 v159, v49, v159
	v_cvt_pk_bf16_f32 v160, v156, v157
	v_cvt_pk_bf16_f32 v161, v158, v159
	v_add_u32_e32 v134, 0x90000, v149
	global_store_dwordx2 v134, v[160:161], s[58:59]
	v_mul_f32_e32 v156, 0xbfb8aa3b, v42
	v_mul_f32_e32 v157, 0xbfb8aa3b, v43
	v_mul_f32_e32 v158, 0xbfb8aa3b, v44
	v_mul_f32_e32 v159, 0xbfb8aa3b, v45
	v_exp_f32_e32 v156, v156
	v_exp_f32_e32 v157, v157
	v_exp_f32_e32 v158, v158
	v_exp_f32_e32 v159, v159
	v_add_f32_e32 v156, 1.0, v156
	v_add_f32_e32 v157, 1.0, v157
	v_add_f32_e32 v158, 1.0, v158
	v_add_f32_e32 v159, 1.0, v159
	v_rcp_f32_e32 v156, v156
	v_rcp_f32_e32 v157, v157
	v_rcp_f32_e32 v158, v158
	v_rcp_f32_e32 v159, v159
	v_mul_f32_e32 v156, v42, v156
	v_mul_f32_e32 v157, v43, v157
	v_mul_f32_e32 v158, v44, v158
	v_mul_f32_e32 v159, v45, v159
	v_cvt_pk_bf16_f32 v160, v156, v157
	v_cvt_pk_bf16_f32 v161, v158, v159
	v_add_u32_e32 v134, 0x90020, v149
	global_store_dwordx2 v134, v[160:161], s[58:59]
	v_mul_f32_e32 v156, 0xbfb8aa3b, v38
	v_mul_f32_e32 v157, 0xbfb8aa3b, v39
	v_mul_f32_e32 v158, 0xbfb8aa3b, v40
	v_mul_f32_e32 v159, 0xbfb8aa3b, v41
	v_exp_f32_e32 v156, v156
	v_exp_f32_e32 v157, v157
	v_exp_f32_e32 v158, v158
	v_exp_f32_e32 v159, v159
	v_add_f32_e32 v156, 1.0, v156
	v_add_f32_e32 v157, 1.0, v157
	v_add_f32_e32 v158, 1.0, v158
	v_add_f32_e32 v159, 1.0, v159
	v_rcp_f32_e32 v156, v156
	v_rcp_f32_e32 v157, v157
	v_rcp_f32_e32 v158, v158
	v_rcp_f32_e32 v159, v159
	v_mul_f32_e32 v156, v38, v156
	v_mul_f32_e32 v157, v39, v157
	v_mul_f32_e32 v158, v40, v158
	v_mul_f32_e32 v159, v41, v159
	v_cvt_pk_bf16_f32 v160, v156, v157
	v_cvt_pk_bf16_f32 v161, v158, v159
	v_add_u32_e32 v134, 0x90100, v149
	global_store_dwordx2 v134, v[160:161], s[58:59]
	v_mul_f32_e32 v156, 0xbfb8aa3b, v34
	v_mul_f32_e32 v157, 0xbfb8aa3b, v35
	v_mul_f32_e32 v158, 0xbfb8aa3b, v36
	v_mul_f32_e32 v159, 0xbfb8aa3b, v37
	v_exp_f32_e32 v156, v156
	v_exp_f32_e32 v157, v157
	v_exp_f32_e32 v158, v158
	v_exp_f32_e32 v159, v159
	v_add_f32_e32 v156, 1.0, v156
	v_add_f32_e32 v157, 1.0, v157
	v_add_f32_e32 v158, 1.0, v158
	v_add_f32_e32 v159, 1.0, v159
	v_rcp_f32_e32 v156, v156
	v_rcp_f32_e32 v157, v157
	v_rcp_f32_e32 v158, v158
	v_rcp_f32_e32 v159, v159
	v_mul_f32_e32 v156, v34, v156
	v_mul_f32_e32 v157, v35, v157
	v_mul_f32_e32 v158, v36, v158
	v_mul_f32_e32 v159, v37, v159
	v_cvt_pk_bf16_f32 v160, v156, v157
	v_cvt_pk_bf16_f32 v161, v158, v159
	v_add_u32_e32 v134, 0x90120, v149
	global_store_dwordx2 v134, v[160:161], s[58:59]
	v_mul_f32_e32 v156, 0xbfb8aa3b, v30
	v_mul_f32_e32 v157, 0xbfb8aa3b, v31
	v_mul_f32_e32 v158, 0xbfb8aa3b, v32
	v_mul_f32_e32 v159, 0xbfb8aa3b, v33
	v_exp_f32_e32 v156, v156
	v_exp_f32_e32 v157, v157
	v_exp_f32_e32 v158, v158
	v_exp_f32_e32 v159, v159
	v_add_f32_e32 v156, 1.0, v156
	v_add_f32_e32 v157, 1.0, v157
	v_add_f32_e32 v158, 1.0, v158
	v_add_f32_e32 v159, 1.0, v159
	v_rcp_f32_e32 v156, v156
	v_rcp_f32_e32 v157, v157
	v_rcp_f32_e32 v158, v158
	v_rcp_f32_e32 v159, v159
	v_mul_f32_e32 v156, v30, v156
	v_mul_f32_e32 v157, v31, v157
	v_mul_f32_e32 v158, v32, v158
	v_mul_f32_e32 v159, v33, v159
	v_cvt_pk_bf16_f32 v160, v156, v157
	v_cvt_pk_bf16_f32 v161, v158, v159
	v_add_u32_e32 v134, 0xa0000, v149
	global_store_dwordx2 v134, v[160:161], s[58:59]
	v_mul_f32_e32 v156, 0xbfb8aa3b, v26
	v_mul_f32_e32 v157, 0xbfb8aa3b, v27
	v_mul_f32_e32 v158, 0xbfb8aa3b, v28
	v_mul_f32_e32 v159, 0xbfb8aa3b, v29
	v_exp_f32_e32 v156, v156
	v_exp_f32_e32 v157, v157
	v_exp_f32_e32 v158, v158
	v_exp_f32_e32 v159, v159
	v_add_f32_e32 v156, 1.0, v156
	v_add_f32_e32 v157, 1.0, v157
	v_add_f32_e32 v158, 1.0, v158
	v_add_f32_e32 v159, 1.0, v159
	v_rcp_f32_e32 v156, v156
	v_rcp_f32_e32 v157, v157
	v_rcp_f32_e32 v158, v158
	v_rcp_f32_e32 v159, v159
	v_mul_f32_e32 v156, v26, v156
	v_mul_f32_e32 v157, v27, v157
	v_mul_f32_e32 v158, v28, v158
	v_mul_f32_e32 v159, v29, v159
	v_cvt_pk_bf16_f32 v160, v156, v157
	v_cvt_pk_bf16_f32 v161, v158, v159
	v_add_u32_e32 v134, 0xa0020, v149
	global_store_dwordx2 v134, v[160:161], s[58:59]
	v_mul_f32_e32 v156, 0xbfb8aa3b, v22
	v_mul_f32_e32 v157, 0xbfb8aa3b, v23
	v_mul_f32_e32 v158, 0xbfb8aa3b, v24
	v_mul_f32_e32 v159, 0xbfb8aa3b, v25
	v_exp_f32_e32 v156, v156
	v_exp_f32_e32 v157, v157
	v_exp_f32_e32 v158, v158
	v_exp_f32_e32 v159, v159
	v_add_f32_e32 v156, 1.0, v156
	v_add_f32_e32 v157, 1.0, v157
	v_add_f32_e32 v158, 1.0, v158
	v_add_f32_e32 v159, 1.0, v159
	v_rcp_f32_e32 v156, v156
	v_rcp_f32_e32 v157, v157
	v_rcp_f32_e32 v158, v158
	v_rcp_f32_e32 v159, v159
	v_mul_f32_e32 v156, v22, v156
	v_mul_f32_e32 v157, v23, v157
	v_mul_f32_e32 v158, v24, v158
	v_mul_f32_e32 v159, v25, v159
	v_cvt_pk_bf16_f32 v160, v156, v157
	v_cvt_pk_bf16_f32 v161, v158, v159
	v_add_u32_e32 v134, 0xa0100, v149
	global_store_dwordx2 v134, v[160:161], s[58:59]
	v_mul_f32_e32 v156, 0xbfb8aa3b, v18
	v_mul_f32_e32 v157, 0xbfb8aa3b, v19
	v_mul_f32_e32 v158, 0xbfb8aa3b, v20
	v_mul_f32_e32 v159, 0xbfb8aa3b, v21
	v_exp_f32_e32 v156, v156
	v_exp_f32_e32 v157, v157
	v_exp_f32_e32 v158, v158
	v_exp_f32_e32 v159, v159
	v_add_f32_e32 v156, 1.0, v156
	v_add_f32_e32 v157, 1.0, v157
	v_add_f32_e32 v158, 1.0, v158
	v_add_f32_e32 v159, 1.0, v159
	v_rcp_f32_e32 v156, v156
	v_rcp_f32_e32 v157, v157
	v_rcp_f32_e32 v158, v158
	v_rcp_f32_e32 v159, v159
	v_mul_f32_e32 v156, v18, v156
	v_mul_f32_e32 v157, v19, v157
	v_mul_f32_e32 v158, v20, v158
	v_mul_f32_e32 v159, v21, v159
	v_cvt_pk_bf16_f32 v160, v156, v157
	v_cvt_pk_bf16_f32 v161, v158, v159
	v_add_u32_e32 v134, 0xa0120, v149
	global_store_dwordx2 v134, v[160:161], s[58:59]
	v_mul_f32_e32 v156, 0xbfb8aa3b, v14
	v_mul_f32_e32 v157, 0xbfb8aa3b, v15
	v_mul_f32_e32 v158, 0xbfb8aa3b, v16
	v_mul_f32_e32 v159, 0xbfb8aa3b, v17
	v_exp_f32_e32 v156, v156
	v_exp_f32_e32 v157, v157
	v_exp_f32_e32 v158, v158
	v_exp_f32_e32 v159, v159
	v_add_f32_e32 v156, 1.0, v156
	v_add_f32_e32 v157, 1.0, v157
	v_add_f32_e32 v158, 1.0, v158
	v_add_f32_e32 v159, 1.0, v159
	v_rcp_f32_e32 v156, v156
	v_rcp_f32_e32 v157, v157
	v_rcp_f32_e32 v158, v158
	v_rcp_f32_e32 v159, v159
	v_mul_f32_e32 v156, v14, v156
	v_mul_f32_e32 v157, v15, v157
	v_mul_f32_e32 v158, v16, v158
	v_mul_f32_e32 v159, v17, v159
	v_cvt_pk_bf16_f32 v160, v156, v157
	v_cvt_pk_bf16_f32 v161, v158, v159
	v_add_u32_e32 v134, 0xb0000, v149
	global_store_dwordx2 v134, v[160:161], s[58:59]
	v_mul_f32_e32 v156, 0xbfb8aa3b, v10
	v_mul_f32_e32 v157, 0xbfb8aa3b, v11
	v_mul_f32_e32 v158, 0xbfb8aa3b, v12
	v_mul_f32_e32 v159, 0xbfb8aa3b, v13
	v_exp_f32_e32 v156, v156
	v_exp_f32_e32 v157, v157
	v_exp_f32_e32 v158, v158
	v_exp_f32_e32 v159, v159
	v_add_f32_e32 v156, 1.0, v156
	v_add_f32_e32 v157, 1.0, v157
	v_add_f32_e32 v158, 1.0, v158
	v_add_f32_e32 v159, 1.0, v159
	v_rcp_f32_e32 v156, v156
	v_rcp_f32_e32 v157, v157
	v_rcp_f32_e32 v158, v158
	v_rcp_f32_e32 v159, v159
	v_mul_f32_e32 v156, v10, v156
	v_mul_f32_e32 v157, v11, v157
	v_mul_f32_e32 v158, v12, v158
	v_mul_f32_e32 v159, v13, v159
	v_cvt_pk_bf16_f32 v160, v156, v157
	v_cvt_pk_bf16_f32 v161, v158, v159
	v_add_u32_e32 v134, 0xb0020, v149
	global_store_dwordx2 v134, v[160:161], s[58:59]
	v_mul_f32_e32 v156, 0xbfb8aa3b, v6
	v_mul_f32_e32 v157, 0xbfb8aa3b, v7
	v_mul_f32_e32 v158, 0xbfb8aa3b, v8
	v_mul_f32_e32 v159, 0xbfb8aa3b, v9
	v_exp_f32_e32 v156, v156
	v_exp_f32_e32 v157, v157
	v_exp_f32_e32 v158, v158
	v_exp_f32_e32 v159, v159
	v_add_f32_e32 v156, 1.0, v156
	v_add_f32_e32 v157, 1.0, v157
	v_add_f32_e32 v158, 1.0, v158
	v_add_f32_e32 v159, 1.0, v159
	v_rcp_f32_e32 v156, v156
	v_rcp_f32_e32 v157, v157
	v_rcp_f32_e32 v158, v158
	v_rcp_f32_e32 v159, v159
	v_mul_f32_e32 v156, v6, v156
	v_mul_f32_e32 v157, v7, v157
	v_mul_f32_e32 v158, v8, v158
	v_mul_f32_e32 v159, v9, v159
	v_cvt_pk_bf16_f32 v160, v156, v157
	v_cvt_pk_bf16_f32 v161, v158, v159
	v_add_u32_e32 v134, 0xb0100, v149
	global_store_dwordx2 v134, v[160:161], s[58:59]
	v_mul_f32_e32 v156, 0xbfb8aa3b, v2
	v_mul_f32_e32 v157, 0xbfb8aa3b, v3
	v_mul_f32_e32 v158, 0xbfb8aa3b, v4
	v_mul_f32_e32 v159, 0xbfb8aa3b, v5
	v_exp_f32_e32 v156, v156
	v_exp_f32_e32 v157, v157
	v_exp_f32_e32 v158, v158
	v_exp_f32_e32 v159, v159
	v_add_f32_e32 v156, 1.0, v156
	v_add_f32_e32 v157, 1.0, v157
	v_add_f32_e32 v158, 1.0, v158
	v_add_f32_e32 v159, 1.0, v159
	v_rcp_f32_e32 v156, v156
	v_rcp_f32_e32 v157, v157
	v_rcp_f32_e32 v158, v158
	v_rcp_f32_e32 v159, v159
	v_mul_f32_e32 v156, v2, v156
	v_mul_f32_e32 v157, v3, v157
	v_mul_f32_e32 v158, v4, v158
	v_mul_f32_e32 v159, v5, v159
	v_cvt_pk_bf16_f32 v160, v156, v157
	v_cvt_pk_bf16_f32 v161, v158, v159
	v_add_u32_e32 v134, 0xb0120, v149
	global_store_dwordx2 v134, v[160:161], s[58:59]
	s_branch .LBB0_470
